# k21 plus code placement: the five GEMM K-loop heads aligned to 64 bytes
# speedup vs baseline: 1.0020x; 1.0020x over previous
;     __device__ bool next(int i, Unit& u) const { if (i >= 2) return false; const int x = c & 7, j = c >> 3; u.pm = 32 * i + 4 * x + (j & 3); u.pn = j >> 2; return true; }
; #define PG8_STAGE(bufoff, gbase, voff) do { _Pragma("unroll") for (int _i = 0; _i < 2; ++_i) \
;         __builtin_amdgcn_global_load_lds((const unsigned*)((const char*)(gbase) + (voff)[_i]), (LAS unsigned*)(lds + (bufoff) + ldsw + _i * 8192), 16, 0, 0); } while (0)
; #define PG8_WAIT_V(n) asm volatile("s_waitcnt vmcnt(" #n ")" ::: "memory")
; #define PG8_WAIT_L(n) asm volatile("s_waitcnt lgkmcnt(" #n ")" ::: "memory")
; template <class Epi, class Sched, bool ALIGN_EPI = true>
; __device__ __forceinline__ void gemm_phase(LAS unsigned char* lds, const Gemm g, const Sched& S, const Epi& E) {
;     ...
;     const char* cA = (const char*)g.A + ((size_t)cur.pm * BM * g.lda + (size_t)cur.pn * g.a_pn_off) * 2; const char* cB = (const char*)g.Bt + (size_t)cur.pn * BM * g.ldb * 2;
;     PG8_STAGE(PG8_SB(0, 0), cB, voffB); PG8_STAGE(PG8_SB(0, 1), cB + hB, voffB); PG8_STAGE(PG8_SA(0, 0), cA, voffA); PG8_STAGE(PG8_SA(0, 1), cA + hA, voffA);
;     if (wr == 1) PG8_BAR;
;     PG8_WAIT_V(2); PG8_BAR;
;     PG8_STAGE(PG8_SB(1, 0), cB + kstep, voffB); PG8_STAGE(PG8_SA(1, 0), cA + kstep, voffA); PG8_STAGE(PG8_SB(1, 1), cB + hB + kstep, voffB);
;     PG8_WAIT_V(6); PG8_BAR;
;     for (;;) {
;         const bool has_next = S.next(ui + 1, nxt);
;         const char* nA = has_next ? (const char*)g.A + ((size_t)nxt.pm * BM * g.lda + (size_t)nxt.pn * g.a_pn_off) * 2 : cA; const char* nB = has_next ? (const char*)g.Bt + (size_t)nxt.pn * BM * g.ldb * 2 : cB;
;         for (int t = 0; t < nt; t += 2) {
;             const bool last = (t == nt - 2);
;             const char* a1 = cA + (size_t)(t + 1) * kstep;
;             const char* a2 = last ? nA : cA + (size_t)(t + 2) * kstep; const char* b2 = last ? nB : cB + (size_t)(t + 2) * kstep;
;             const char* a3 = a2 + kstep; const char* b3 = b2 + kstep;
;             PG8_LDB(B0, 0, 0); PG8_LDB(B1, 0, 1); PG8_SCHED; PG8_LDA(At, 0, 0); PG8_STAGE(PG8_SA(1, 1), a1 + hA, voffA);
;             PG8_WAIT_V(8); PG8_WAIT_L(0); PG8_BAR; PG8_MMA(0, 0, At, B0); PG8_MMA(0, 1, At, B1); PG8_BAR; PG8_SCHED;
;             PG8_LDA(At, 0, 1); PG8_STAGE(PG8_SB(0, 0), b2, voffB); PG8_STAGE(PG8_SB(0, 1), b2 + hB, voffB); PG8_STAGE(PG8_SA(0, 0), a2, voffA);
.LBB0_76:
	s_ashr_i32 s15, s14, 31
	s_lshl_b64 s[18:19], s[14:15], 20
	s_add_u32 s38, s46, s18
	s_addc_u32 s39, s47, s19
	s_and_b64 s[18:19], s[4:5], exec
	s_cselect_b32 s15, s39, s7
	s_cselect_b32 s17, s38, s6
	s_ashr_i32 s13, s12, 31
	s_lshl_b64 s[18:19], s[12:13], 20
	s_add_u32 s40, s53, s18
	s_addc_u32 s41, s58, s19
	s_and_b64 s[18:19], s[4:5], exec
	s_cselect_b32 s13, s41, s43
	s_cselect_b32 s18, s40, s42
	s_add_u32 s6, s6, 0x80080
	s_addc_u32 s7, s7, 0
	s_add_u32 s19, s42, 0x100
	s_addc_u32 s24, s43, 0
	s_mov_b32 s25, -2
	s_add_u32 s26, s6, 0xfff80080
	s_addc_u32 s27, s7, -1
	s_add_i32 s30, 0, 0x10000
	s_cmp_eq_u32 s25, 28
	s_cselect_b32 s45, s15, s27
	s_cselect_b32 s44, s17, s26
	s_cselect_b32 s43, s13, s24
	s_cselect_b32 s42, s18, s19
	s_add_i32 s31, 0, 0x14000
	v_add_u32_e32 v144, s30, v166
	v_add_u32_e32 v156, s31, v166
	ds_read_b128 v[132:135], v144
	ds_read_b128 v[136:139], v144 offset:1024
	ds_read_b128 v[140:143], v144 offset:2048
	ds_read_b128 v[144:147], v144 offset:3072
	ds_read_b128 v[170:173], v156
	ds_read_b128 v[174:177], v156 offset:1024
	ds_read_b128 v[178:181], v156 offset:2048
	ds_read_b128 v[182:185], v156 offset:3072
	v_lshl_add_u64 v[156:157], s[6:7], 0, v[152:153]
	s_add_i32 m0, s60, 0xc000
	ds_read_b128 v[186:189], v168
	ds_read_b128 v[190:193], v168 offset:1024
	ds_read_b128 v[194:197], v168 offset:2048
	ds_read_b128 v[204:207], v168 offset:3072
	ds_read_b128 v[208:211], v168 offset:4096
	ds_read_b128 v[212:215], v168 offset:5120
	ds_read_b128 v[216:219], v168 offset:6144
	ds_read_b128 v[220:223], v168 offset:7168
	global_load_lds_dwordx4 v[156:157], off
	v_lshl_add_u64 v[156:157], s[6:7], 0, v[154:155]
	s_add_i32 m0, s60, 0xe000
	s_nop 0
	global_load_lds_dwordx4 v[156:157], off
	s_waitcnt vmcnt(8)
	s_waitcnt lgkmcnt(0)
	s_barrier
	s_setprio 1
	s_waitcnt lgkmcnt(0)
	v_mfma_f32_16x16x32_bf16 v[128:131], v[132:135], v[186:189], 0
	v_mfma_f32_16x16x32_bf16 v[128:131], v[136:139], v[190:193], v[128:131]
	v_mfma_f32_16x16x32_bf16 v[124:127], v[140:143], v[186:189], 0
	v_mfma_f32_16x16x32_bf16 v[124:127], v[144:147], v[190:193], v[124:127]
	v_mfma_f32_16x16x32_bf16 v[116:119], v[132:135], v[194:197], 0
	v_mfma_f32_16x16x32_bf16 v[116:119], v[136:139], v[204:207], v[116:119]
	v_mfma_f32_16x16x32_bf16 v[112:115], v[140:143], v[194:197], 0
	v_mfma_f32_16x16x32_bf16 v[112:115], v[144:147], v[204:207], v[112:115]
	v_mfma_f32_16x16x32_bf16 v[104:107], v[132:135], v[208:211], 0
	v_mfma_f32_16x16x32_bf16 v[104:107], v[136:139], v[212:215], v[104:107]
	v_mfma_f32_16x16x32_bf16 v[96:99], v[140:143], v[208:211], 0
	v_mfma_f32_16x16x32_bf16 v[96:99], v[144:147], v[212:215], v[96:99]
	v_mfma_f32_16x16x32_bf16 v[88:91], v[132:135], v[216:219], 0
	v_mfma_f32_16x16x32_bf16 v[88:91], v[136:139], v[220:223], v[88:91]
	v_mfma_f32_16x16x32_bf16 v[80:83], v[140:143], v[216:219], 0
	v_mfma_f32_16x16x32_bf16 v[80:83], v[144:147], v[220:223], v[80:83]
	s_setprio 0
	s_setprio 1
	v_mfma_f32_16x16x32_bf16 v[120:123], v[170:173], v[186:189], 0
	v_mfma_f32_16x16x32_bf16 v[120:123], v[174:177], v[190:193], v[120:123]
	v_mfma_f32_16x16x32_bf16 v[108:111], v[178:181], v[186:189], 0
	v_mfma_f32_16x16x32_bf16 v[108:111], v[182:185], v[190:193], v[108:111]
	v_mfma_f32_16x16x32_bf16 v[100:103], v[170:173], v[194:197], 0
	v_mfma_f32_16x16x32_bf16 v[100:103], v[174:177], v[204:207], v[100:103]
	v_mfma_f32_16x16x32_bf16 v[92:95], v[178:181], v[194:197], 0
	v_mfma_f32_16x16x32_bf16 v[92:95], v[182:185], v[204:207], v[92:95]
	v_mfma_f32_16x16x32_bf16 v[84:87], v[170:173], v[208:211], 0
	v_mfma_f32_16x16x32_bf16 v[84:87], v[174:177], v[212:215], v[84:87]
	v_mfma_f32_16x16x32_bf16 v[76:79], v[178:181], v[208:211], 0
	v_mfma_f32_16x16x32_bf16 v[76:79], v[182:185], v[212:215], v[76:79]
	v_mfma_f32_16x16x32_bf16 v[72:75], v[170:173], v[216:219], 0
	v_mfma_f32_16x16x32_bf16 v[72:75], v[174:177], v[220:223], v[72:75]
	s_setprio 2
	s_barrier
	v_mfma_f32_16x16x32_bf16 v[68:71], v[178:181], v[216:219], 0
	v_mfma_f32_16x16x32_bf16 v[68:71], v[182:185], v[220:223], v[68:71]
	s_setprio 0
	s_add_i32 s26, s30, s59
	v_lshl_add_u64 v[156:157], s[42:43], 0, v[2:3]
	s_mov_b32 m0, s26
	ds_read_b128 v[186:189], v168 offset:16384
	ds_read_b128 v[190:193], v168 offset:17408
	ds_read_b128 v[194:197], v168 offset:18432
	ds_read_b128 v[204:207], v168 offset:19456
	ds_read_b128 v[208:211], v168 offset:20480
	ds_read_b128 v[212:215], v168 offset:21504
	ds_read_b128 v[216:219], v168 offset:22528
	ds_read_b128 v[220:223], v168 offset:23552
	global_load_lds_dwordx4 v[156:157], off
	s_add_i32 m0, s26, 0x2000
	s_add_u32 s26, s42, 0x80000
	v_lshl_add_u64 v[164:165], s[42:43], 0, v[0:1]
	s_addc_u32 s27, s43, 0
	s_add_i32 s30, s31, s59
	global_load_lds_dwordx4 v[164:165], off
	v_lshl_add_u64 v[224:225], s[26:27], 0, v[2:3]
	s_mov_b32 m0, s30
	v_lshl_add_u64 v[226:227], s[44:45], 0, v[148:149]
	global_load_lds_dwordx4 v[224:225], off
	v_lshl_add_u64 v[224:225], s[26:27], 0, v[0:1]
	s_add_i32 m0, s30, 0x2000
	s_nop 0
	global_load_lds_dwordx4 v[224:225], off
	v_lshl_add_u64 v[224:225], s[44:45], 0, v[150:151]
	s_mov_b32 m0, s60
	s_nop 0
	global_load_lds_dwordx4 v[224:225], off
	s_mov_b32 m0, s61
	s_nop 0
	global_load_lds_dwordx4 v[226:227], off
	s_waitcnt vmcnt(8)
	s_waitcnt lgkmcnt(0)
	s_barrier
; #define PG8_STAGE(bufoff, gbase, voff) do { _Pragma("unroll") for (int _i = 0; _i < 2; ++_i) \
;         __builtin_amdgcn_global_load_lds((const unsigned*)((const char*)(gbase) + (voff)[_i]), (LAS unsigned*)(lds + (bufoff) + ldsw + _i * 8192), 16, 0, 0); } while (0)
; #define PG8_LDA(dst, b, h) do { _Pragma("unroll") for (int m = 0; m < 4; ++m) _Pragma("unroll") for (int k = 0; k < 2; ++k) dst[m][k] = *(const LAS bf16x8*)(lds + PG8_SA(b, h) + aoff + m * 2048 + k * 1024); } while (0)
; #define PG8_LDB(dst, b, h) do { _Pragma("unroll") for (int n = 0; n < 2; ++n) _Pragma("unroll") for (int k = 0; k < 2; ++k) dst[n][k] = *(const LAS bf16x8*)(lds + PG8_SB(b, h) + boff + n * 2048 + k * 1024); } while (0)
; #define PG8_MMA(ai, bj, At, Bt) do { __builtin_amdgcn_s_setprio(1); _Pragma("unroll") for (int m = 0; m < 4; ++m) _Pragma("unroll") for (int n = 0; n < 2; ++n) _Pragma("unroll") for (int k = 0; k < 2; ++k) \
;         acc[ai][bj][m][n] = __builtin_amdgcn_mfma_f32_16x16x32_bf16(Bt[n][k], At[m][k], acc[ai][bj][m][n], 0, 0, 0); __builtin_amdgcn_s_setprio(0); } while (0)
; #define PG8_WAIT_V(n) asm volatile("s_waitcnt vmcnt(" #n ")" ::: "memory")
; #define PG8_BAR __builtin_amdgcn_s_barrier()
; template <class Epi, class Sched, bool ALIGN_EPI = true>
; __device__ __forceinline__ void gemm_phase(LAS unsigned char* lds, const Gemm g, const Sched& S, const Epi& E) {
;     ...
;             PG8_LDB(B0, 0, 0); PG8_LDB(B1, 0, 1); PG8_SCHED; PG8_LDA(At, 0, 0); PG8_STAGE(PG8_SA(1, 1), a1 + hA, voffA);
;             PG8_WAIT_V(8); PG8_WAIT_L(0); PG8_BAR; PG8_MMA(0, 0, At, B0); PG8_MMA(0, 1, At, B1); PG8_BAR; PG8_SCHED;
;             PG8_LDA(At, 0, 1); PG8_STAGE(PG8_SB(0, 0), b2, voffB); PG8_STAGE(PG8_SB(0, 1), b2 + hB, voffB); PG8_STAGE(PG8_SA(0, 0), a2, voffA);
;             PG8_WAIT_V(8); PG8_WAIT_L(0); PG8_BAR; PG8_MMA(1, 0, At, B0); PG8_MMA(1, 1, At, B1); PG8_BAR; PG8_SCHED;
;             PG8_LDB(B0, 1, 0); PG8_LDB(B1, 1, 1); PG8_SCHED; PG8_LDA(At, 1, 0); PG8_STAGE(PG8_SA(0, 1), a2 + hA, voffA);
;             PG8_WAIT_V(8); PG8_WAIT_L(0); PG8_BAR; PG8_MMA(0, 0, At, B0); PG8_MMA(0, 1, At, B1); PG8_BAR; PG8_SCHED;
;             PG8_LDA(At, 1, 1); PG8_STAGE(PG8_SB(1, 0), b3, voffB); PG8_STAGE(PG8_SB(1, 1), b3 + hB, voffB); PG8_STAGE(PG8_SA(1, 0), a3, voffA);
;             PG8_WAIT_V(8); PG8_WAIT_L(0); PG8_BAR; PG8_MMA(1, 0, At, B0); PG8_MMA(1, 1, At, B1); PG8_BAR; PG8_SCHED;
	s_setprio 1
	s_waitcnt lgkmcnt(0)
	v_mfma_f32_16x16x32_bf16 v[64:67], v[132:135], v[186:189], 0
	v_mfma_f32_16x16x32_bf16 v[64:67], v[136:139], v[190:193], v[64:67]
	v_mfma_f32_16x16x32_bf16 v[60:63], v[140:143], v[186:189], 0
	v_mfma_f32_16x16x32_bf16 v[60:63], v[144:147], v[190:193], v[60:63]
	v_mfma_f32_16x16x32_bf16 v[56:59], v[132:135], v[194:197], 0
	v_mfma_f32_16x16x32_bf16 v[56:59], v[136:139], v[204:207], v[56:59]
	v_mfma_f32_16x16x32_bf16 v[48:51], v[140:143], v[194:197], 0
	v_mfma_f32_16x16x32_bf16 v[48:51], v[144:147], v[204:207], v[48:51]
	v_mfma_f32_16x16x32_bf16 v[40:43], v[132:135], v[208:211], 0
	v_mfma_f32_16x16x32_bf16 v[40:43], v[136:139], v[212:215], v[40:43]
	v_mfma_f32_16x16x32_bf16 v[32:35], v[140:143], v[208:211], 0
	v_mfma_f32_16x16x32_bf16 v[32:35], v[144:147], v[212:215], v[32:35]
	v_mfma_f32_16x16x32_bf16 v[24:27], v[132:135], v[216:219], 0
	v_mfma_f32_16x16x32_bf16 v[24:27], v[136:139], v[220:223], v[24:27]
	v_mfma_f32_16x16x32_bf16 v[16:19], v[140:143], v[216:219], 0
	v_mfma_f32_16x16x32_bf16 v[16:19], v[144:147], v[220:223], v[16:19]
	s_setprio 0
	s_setprio 1
	v_mfma_f32_16x16x32_bf16 v[52:55], v[170:173], v[186:189], 0
	v_mfma_f32_16x16x32_bf16 v[52:55], v[174:177], v[190:193], v[52:55]
	v_mfma_f32_16x16x32_bf16 v[44:47], v[178:181], v[186:189], 0
	v_mfma_f32_16x16x32_bf16 v[44:47], v[182:185], v[190:193], v[44:47]
	v_mfma_f32_16x16x32_bf16 v[36:39], v[170:173], v[194:197], 0
	v_mfma_f32_16x16x32_bf16 v[36:39], v[174:177], v[204:207], v[36:39]
	v_mfma_f32_16x16x32_bf16 v[28:31], v[178:181], v[194:197], 0
	v_mfma_f32_16x16x32_bf16 v[28:31], v[182:185], v[204:207], v[28:31]
	v_mfma_f32_16x16x32_bf16 v[20:23], v[170:173], v[208:211], 0
	v_mfma_f32_16x16x32_bf16 v[20:23], v[174:177], v[212:215], v[20:23]
	v_mfma_f32_16x16x32_bf16 v[12:15], v[178:181], v[208:211], 0
	v_mfma_f32_16x16x32_bf16 v[12:15], v[182:185], v[212:215], v[12:15]
	v_mfma_f32_16x16x32_bf16 v[8:11], v[170:173], v[216:219], 0
	v_mfma_f32_16x16x32_bf16 v[8:11], v[174:177], v[220:223], v[8:11]
	s_setprio 2
	s_barrier
	v_mfma_f32_16x16x32_bf16 v[4:7], v[178:181], v[216:219], 0
	v_mfma_f32_16x16x32_bf16 v[4:7], v[182:185], v[220:223], v[4:7]
	s_setprio 0
	s_add_i32 s30, 0, 0x18000
	s_add_i32 s31, 0, 0x1c000
	v_add_u32_e32 v144, s30, v166
	v_add_u32_e32 v160, s31, v166
	ds_read_b128 v[132:135], v144
	ds_read_b128 v[136:139], v144 offset:1024
	ds_read_b128 v[140:143], v144 offset:2048
	ds_read_b128 v[144:147], v144 offset:3072
	ds_read_b128 v[170:173], v160
	ds_read_b128 v[174:177], v160 offset:1024
	ds_read_b128 v[178:181], v160 offset:2048
	ds_read_b128 v[182:185], v160 offset:3072
	s_add_u32 s26, s44, 0x80000
	s_addc_u32 s27, s45, 0
	s_mov_b32 m0, s62
	v_lshl_add_u64 v[228:229], s[26:27], 0, v[150:151]
	ds_read_b128 v[186:189], v168 offset:32768
	ds_read_b128 v[190:193], v168 offset:33792
	ds_read_b128 v[194:197], v168 offset:34816
	ds_read_b128 v[204:207], v168 offset:35840
	ds_read_b128 v[208:211], v168 offset:36864
	ds_read_b128 v[212:215], v168 offset:37888
	ds_read_b128 v[216:219], v168 offset:38912
	ds_read_b128 v[220:223], v168 offset:39936
	global_load_lds_dwordx4 v[228:229], off
	v_lshl_add_u64 v[228:229], s[26:27], 0, v[148:149]
	s_mov_b32 m0, s63
	s_nop 0
	global_load_lds_dwordx4 v[228:229], off
	s_waitcnt vmcnt(8)
	s_waitcnt lgkmcnt(0)
	s_barrier
	s_setprio 1
	s_waitcnt lgkmcnt(0)
	v_mfma_f32_16x16x32_bf16 v[128:131], v[132:135], v[186:189], v[128:131]
	v_mfma_f32_16x16x32_bf16 v[128:131], v[136:139], v[190:193], v[128:131]
	v_mfma_f32_16x16x32_bf16 v[124:127], v[140:143], v[186:189], v[124:127]
	v_mfma_f32_16x16x32_bf16 v[124:127], v[144:147], v[190:193], v[124:127]
	v_mfma_f32_16x16x32_bf16 v[116:119], v[132:135], v[194:197], v[116:119]
	v_mfma_f32_16x16x32_bf16 v[116:119], v[136:139], v[204:207], v[116:119]
	v_mfma_f32_16x16x32_bf16 v[112:115], v[140:143], v[194:197], v[112:115]
	v_mfma_f32_16x16x32_bf16 v[112:115], v[144:147], v[204:207], v[112:115]
	v_mfma_f32_16x16x32_bf16 v[104:107], v[132:135], v[208:211], v[104:107]
	v_mfma_f32_16x16x32_bf16 v[104:107], v[136:139], v[212:215], v[104:107]
	v_mfma_f32_16x16x32_bf16 v[96:99], v[140:143], v[208:211], v[96:99]
	v_mfma_f32_16x16x32_bf16 v[96:99], v[144:147], v[212:215], v[96:99]
	v_mfma_f32_16x16x32_bf16 v[88:91], v[132:135], v[216:219], v[88:91]
	v_mfma_f32_16x16x32_bf16 v[88:91], v[136:139], v[220:223], v[88:91]
	v_mfma_f32_16x16x32_bf16 v[80:83], v[140:143], v[216:219], v[80:83]
	v_mfma_f32_16x16x32_bf16 v[80:83], v[144:147], v[220:223], v[80:83]
	s_setprio 0
	s_setprio 1
	v_mfma_f32_16x16x32_bf16 v[120:123], v[170:173], v[186:189], v[120:123]
	v_mfma_f32_16x16x32_bf16 v[120:123], v[174:177], v[190:193], v[120:123]
	v_mfma_f32_16x16x32_bf16 v[108:111], v[178:181], v[186:189], v[108:111]
	v_mfma_f32_16x16x32_bf16 v[108:111], v[182:185], v[190:193], v[108:111]
	v_mfma_f32_16x16x32_bf16 v[100:103], v[170:173], v[194:197], v[100:103]
	v_mfma_f32_16x16x32_bf16 v[100:103], v[174:177], v[204:207], v[100:103]
	v_mfma_f32_16x16x32_bf16 v[92:95], v[178:181], v[194:197], v[92:95]
	v_mfma_f32_16x16x32_bf16 v[92:95], v[182:185], v[204:207], v[92:95]
	v_mfma_f32_16x16x32_bf16 v[84:87], v[170:173], v[208:211], v[84:87]
	v_mfma_f32_16x16x32_bf16 v[84:87], v[174:177], v[212:215], v[84:87]
	v_mfma_f32_16x16x32_bf16 v[76:79], v[178:181], v[208:211], v[76:79]
	v_mfma_f32_16x16x32_bf16 v[76:79], v[182:185], v[212:215], v[76:79]
	v_mfma_f32_16x16x32_bf16 v[72:75], v[170:173], v[216:219], v[72:75]
	v_mfma_f32_16x16x32_bf16 v[72:75], v[174:177], v[220:223], v[72:75]
	s_setprio 2
	s_barrier
; #define PG8_STAGE(bufoff, gbase, voff) do { _Pragma("unroll") for (int _i = 0; _i < 2; ++_i) \
;         __builtin_amdgcn_global_load_lds((const unsigned*)((const char*)(gbase) + (voff)[_i]), (LAS unsigned*)(lds + (bufoff) + ldsw + _i * 8192), 16, 0, 0); } while (0)
; #define PG8_LDA(dst, b, h) do { _Pragma("unroll") for (int m = 0; m < 4; ++m) _Pragma("unroll") for (int k = 0; k < 2; ++k) dst[m][k] = *(const LAS bf16x8*)(lds + PG8_SA(b, h) + aoff + m * 2048 + k * 1024); } while (0)
; #define PG8_LDB(dst, b, h) do { _Pragma("unroll") for (int n = 0; n < 2; ++n) _Pragma("unroll") for (int k = 0; k < 2; ++k) dst[n][k] = *(const LAS bf16x8*)(lds + PG8_SB(b, h) + boff + n * 2048 + k * 1024); } while (0)
; #define PG8_WAIT_V(n) asm volatile("s_waitcnt vmcnt(" #n ")" ::: "memory")
; #define PG8_WAIT_L(n) asm volatile("s_waitcnt lgkmcnt(" #n ")" ::: "memory")
; #define PG8_BAR __builtin_amdgcn_s_barrier()
; template <class Epi, class Sched, bool ALIGN_EPI = true>
; __device__ __forceinline__ void gemm_phase(LAS unsigned char* lds, const Gemm g, const Sched& S, const Epi& E) {
;     ...
;             const char* a1 = cA + (size_t)(t + 1) * kstep;
;             const char* a2 = last ? nA : cA + (size_t)(t + 2) * kstep; const char* b2 = last ? nB : cB + (size_t)(t + 2) * kstep;
;             const char* a3 = a2 + kstep; const char* b3 = b2 + kstep;
;             PG8_LDB(B0, 0, 0); PG8_LDB(B1, 0, 1); PG8_SCHED; PG8_LDA(At, 0, 0); PG8_STAGE(PG8_SA(1, 1), a1 + hA, voffA);
;             PG8_WAIT_V(8); PG8_WAIT_L(0); PG8_BAR; PG8_MMA(0, 0, At, B0); PG8_MMA(0, 1, At, B1); PG8_BAR; PG8_SCHED;
;             PG8_LDA(At, 0, 1); PG8_STAGE(PG8_SB(0, 0), b2, voffB); PG8_STAGE(PG8_SB(0, 1), b2 + hB, voffB); PG8_STAGE(PG8_SA(0, 0), a2, voffA);
;             PG8_WAIT_V(8); PG8_WAIT_L(0); PG8_BAR; PG8_MMA(1, 0, At, B0); PG8_MMA(1, 1, At, B1); PG8_BAR; PG8_SCHED;
;             PG8_LDB(B0, 1, 0); PG8_LDB(B1, 1, 1); PG8_SCHED; PG8_LDA(At, 1, 0); PG8_STAGE(PG8_SA(0, 1), a2 + hA, voffA);
;             PG8_WAIT_V(8); PG8_WAIT_L(0); PG8_BAR; PG8_MMA(0, 0, At, B0); PG8_MMA(0, 1, At, B1); PG8_BAR; PG8_SCHED;
;             PG8_LDA(At, 1, 1); PG8_STAGE(PG8_SB(1, 0), b3, voffB); PG8_STAGE(PG8_SB(1, 1), b3 + hB, voffB); PG8_STAGE(PG8_SA(1, 0), a3, voffA);
;             PG8_WAIT_V(8); PG8_WAIT_L(0); PG8_BAR; PG8_MMA(1, 0, At, B0); PG8_MMA(1, 1, At, B1); PG8_BAR; PG8_SCHED;
	v_mfma_f32_16x16x32_bf16 v[68:71], v[178:181], v[216:219], v[68:71]
	v_mfma_f32_16x16x32_bf16 v[68:71], v[182:185], v[220:223], v[68:71]
	s_setprio 0
	s_add_i32 s26, s30, s59
	v_lshl_add_u64 v[156:157], v[156:157], 0, s[86:87]
	s_mov_b32 m0, s26
	ds_read_b128 v[186:189], v168 offset:49152
	ds_read_b128 v[190:193], v168 offset:50176
	ds_read_b128 v[194:197], v168 offset:51200
	ds_read_b128 v[204:207], v168 offset:52224
	ds_read_b128 v[208:211], v168 offset:53248
	ds_read_b128 v[212:215], v168 offset:54272
	ds_read_b128 v[216:219], v168 offset:55296
	ds_read_b128 v[220:223], v168 offset:56320
	global_load_lds_dwordx4 v[156:157], off
	s_add_i32 m0, s26, 0x2000
	s_add_u32 s26, s42, 0x80080
	v_lshl_add_u64 v[156:157], v[164:165], 0, s[86:87]
	s_addc_u32 s27, s43, 0
	s_add_i32 s30, s31, s59
	global_load_lds_dwordx4 v[156:157], off
	v_lshl_add_u64 v[156:157], s[26:27], 0, v[2:3]
	s_mov_b32 m0, s30
	s_nop 0
	global_load_lds_dwordx4 v[156:157], off
	v_lshl_add_u64 v[156:157], s[26:27], 0, v[0:1]
	s_add_i32 m0, s30, 0x2000
	s_nop 0
	global_load_lds_dwordx4 v[156:157], off
	v_lshl_add_u64 v[156:157], v[224:225], 0, s[86:87]
	s_mov_b32 m0, s64
	s_nop 0
	global_load_lds_dwordx4 v[156:157], off
	v_lshl_add_u64 v[156:157], v[226:227], 0, s[86:87]
	s_mov_b32 m0, s65
	s_nop 0
	global_load_lds_dwordx4 v[156:157], off
	s_waitcnt vmcnt(8)
	s_waitcnt lgkmcnt(0)
	s_barrier
	s_setprio 1
	s_waitcnt lgkmcnt(0)
	v_mfma_f32_16x16x32_bf16 v[64:67], v[132:135], v[186:189], v[64:67]
	v_mfma_f32_16x16x32_bf16 v[64:67], v[136:139], v[190:193], v[64:67]
	s_add_i32 s25, s25, 2
	s_add_u32 s6, s6, 0x100
	v_mfma_f32_16x16x32_bf16 v[60:63], v[140:143], v[186:189], v[60:63]
	v_mfma_f32_16x16x32_bf16 v[60:63], v[144:147], v[190:193], v[60:63]
	s_addc_u32 s7, s7, 0
	s_add_u32 s19, s19, 0x100
	v_mfma_f32_16x16x32_bf16 v[56:59], v[132:135], v[194:197], v[56:59]
	v_mfma_f32_16x16x32_bf16 v[56:59], v[136:139], v[204:207], v[56:59]
	s_addc_u32 s24, s24, 0
	s_add_u32 s26, s6, 0xfff80080
	v_mfma_f32_16x16x32_bf16 v[48:51], v[140:143], v[194:197], v[48:51]
	v_mfma_f32_16x16x32_bf16 v[48:51], v[144:147], v[204:207], v[48:51]
	s_addc_u32 s27, s7, -1
	s_add_i32 s30, 0, 0x10000
	v_mfma_f32_16x16x32_bf16 v[40:43], v[132:135], v[208:211], v[40:43]
	v_mfma_f32_16x16x32_bf16 v[40:43], v[136:139], v[212:215], v[40:43]
	s_cmp_eq_u32 s25, 28
	s_cselect_b32 s45, s15, s27
	v_mfma_f32_16x16x32_bf16 v[32:35], v[140:143], v[208:211], v[32:35]
	v_mfma_f32_16x16x32_bf16 v[32:35], v[144:147], v[212:215], v[32:35]
	s_cselect_b32 s44, s17, s26
	s_cselect_b32 s43, s13, s24
	v_mfma_f32_16x16x32_bf16 v[24:27], v[132:135], v[216:219], v[24:27]
	v_mfma_f32_16x16x32_bf16 v[24:27], v[136:139], v[220:223], v[24:27]
	s_cselect_b32 s42, s18, s19
	s_add_i32 s31, 0, 0x14000
	v_mfma_f32_16x16x32_bf16 v[16:19], v[140:143], v[216:219], v[16:19]
	v_mfma_f32_16x16x32_bf16 v[16:19], v[144:147], v[220:223], v[16:19]
	s_setprio 0
	s_setprio 1
	v_mfma_f32_16x16x32_bf16 v[52:55], v[170:173], v[186:189], v[52:55]
	v_mfma_f32_16x16x32_bf16 v[52:55], v[174:177], v[190:193], v[52:55]
	v_mfma_f32_16x16x32_bf16 v[44:47], v[178:181], v[186:189], v[44:47]
	v_mfma_f32_16x16x32_bf16 v[44:47], v[182:185], v[190:193], v[44:47]
	v_mfma_f32_16x16x32_bf16 v[36:39], v[170:173], v[194:197], v[36:39]
	v_mfma_f32_16x16x32_bf16 v[36:39], v[174:177], v[204:207], v[36:39]
	v_mfma_f32_16x16x32_bf16 v[28:31], v[178:181], v[194:197], v[28:31]
	v_mfma_f32_16x16x32_bf16 v[28:31], v[182:185], v[204:207], v[28:31]
	v_mfma_f32_16x16x32_bf16 v[20:23], v[170:173], v[208:211], v[20:23]
	v_mfma_f32_16x16x32_bf16 v[20:23], v[174:177], v[212:215], v[20:23]
	v_mfma_f32_16x16x32_bf16 v[12:15], v[178:181], v[208:211], v[12:15]
	v_mfma_f32_16x16x32_bf16 v[12:15], v[182:185], v[212:215], v[12:15]
	v_mfma_f32_16x16x32_bf16 v[8:11], v[170:173], v[216:219], v[8:11]
	v_mfma_f32_16x16x32_bf16 v[8:11], v[174:177], v[220:223], v[8:11]
	s_setprio 2
	s_barrier
	v_mfma_f32_16x16x32_bf16 v[4:7], v[178:181], v[216:219], v[4:7]
	v_mfma_f32_16x16x32_bf16 v[4:7], v[182:185], v[220:223], v[4:7]
	s_setprio 0
	s_cmp_gt_u32 s25, 29
	s_cbranch_scc1 .Lpeel_exit_77
	.p2align	6

;     __device__ bool next(int i, Unit& u) const { if (i >= 2) return false; const int x = c & 7, j = c >> 3; u.pm = 32 * i + 4 * x + (j & 3); u.pn = j >> 2; return true; }
; #define PG8_STAGE(bufoff, gbase, voff) do { _Pragma("unroll") for (int _i = 0; _i < 2; ++_i) \
;         __builtin_amdgcn_global_load_lds((const unsigned*)((const char*)(gbase) + (voff)[_i]), (LAS unsigned*)(lds + (bufoff) + ldsw + _i * 8192), 16, 0, 0); } while (0)
; #define PG8_LDA(dst, b, h) do { _Pragma("unroll") for (int m = 0; m < 4; ++m) _Pragma("unroll") for (int k = 0; k < 2; ++k) dst[m][k] = *(const LAS bf16x8*)(lds + PG8_SA(b, h) + aoff + m * 2048 + k * 1024); } while (0)
; #define PG8_LDB(dst, b, h) do { _Pragma("unroll") for (int n = 0; n < 2; ++n) _Pragma("unroll") for (int k = 0; k < 2; ++k) dst[n][k] = *(const LAS bf16x8*)(lds + PG8_SB(b, h) + boff + n * 2048 + k * 1024); } while (0)
; #define PG8_WAIT_V(n) asm volatile("s_waitcnt vmcnt(" #n ")" ::: "memory")
; #define PG8_WAIT_L(n) asm volatile("s_waitcnt lgkmcnt(" #n ")" ::: "memory")
; #define PG8_BAR __builtin_amdgcn_s_barrier()
; template <class Epi, class Sched, bool ALIGN_EPI = true>
; __device__ __forceinline__ void gemm_phase(LAS unsigned char* lds, const Gemm g, const Sched& S, const Epi& E) {
;     ...
;         const bool has_next = S.next(ui + 1, nxt);
;         const char* nA = has_next ? (const char*)g.A + ((size_t)nxt.pm * BM * g.lda + (size_t)nxt.pn * g.a_pn_off) * 2 : cA; const char* nB = has_next ? (const char*)g.Bt + (size_t)nxt.pn * BM * g.ldb * 2 : cB;
;         for (int t = 0; t < nt; t += 2) {
;             const bool last = (t == nt - 2);
;             const char* a1 = cA + (size_t)(t + 1) * kstep;
;             const char* a2 = last ? nA : cA + (size_t)(t + 2) * kstep; const char* b2 = last ? nB : cB + (size_t)(t + 2) * kstep;
;             const char* a3 = a2 + kstep; const char* b3 = b2 + kstep;
;             PG8_LDB(B0, 0, 0); PG8_LDB(B1, 0, 1); PG8_SCHED; PG8_LDA(At, 0, 0); PG8_STAGE(PG8_SA(1, 1), a1 + hA, voffA);
;             PG8_WAIT_V(8); PG8_WAIT_L(0); PG8_BAR; PG8_MMA(0, 0, At, B0); PG8_MMA(0, 1, At, B1); PG8_BAR; PG8_SCHED;
;             PG8_LDA(At, 0, 1); PG8_STAGE(PG8_SB(0, 0), b2, voffB); PG8_STAGE(PG8_SB(0, 1), b2 + hB, voffB); PG8_STAGE(PG8_SA(0, 0), a2, voffA);
;             PG8_WAIT_V(8); PG8_WAIT_L(0); PG8_BAR; PG8_MMA(1, 0, At, B0); PG8_MMA(1, 1, At, B1); PG8_BAR; PG8_SCHED;
.LBB0_217:
	s_ashr_i32 s11, s10, 31
	s_lshl_b64 s[12:13], s[10:11], 20
	s_add_u32 s12, s46, s12
	s_addc_u32 s13, s47, s13
	s_and_b64 s[14:15], s[4:5], exec
	s_cselect_b32 s11, s13, s39
	s_cselect_b32 s18, s12, s38
	s_ashr_i32 s9, s8, 31
	s_lshl_b64 s[14:15], s[8:9], 20
	s_add_u32 s14, s44, s14
	s_addc_u32 s15, s45, s15
	s_and_b64 s[24:25], s[4:5], exec
	s_cselect_b32 s9, s15, s41
	s_cselect_b32 s19, s14, s40
	s_add_u32 s38, s38, 0x80080
	s_addc_u32 s39, s39, 0
	s_add_u32 s24, s40, 0x100
	s_addc_u32 s25, s41, 0
	s_mov_b32 s26, -2
	s_add_u32 s27, s38, 0xfff80080
	s_addc_u32 s30, s39, -1
	s_add_i32 s31, 0, 0x10000
	s_cmp_eq_u32 s26, 28
	s_cselect_b32 s43, s11, s30
	s_cselect_b32 s42, s18, s27
	v_add_u32_e32 v156, s31, v145
	s_cselect_b32 s41, s9, s25
	s_cselect_b32 s40, s19, s24
	s_add_i32 s27, 0, 0x14000
	ds_read_b128 v[140:143], v156
	ds_read_b128 v[148:151], v156 offset:1024
	ds_read_b128 v[152:155], v156 offset:2048
	ds_read_b128 v[164:167], v156 offset:3072
	v_add_u32_e32 v156, s27, v145
	ds_read_b128 v[168:171], v156
	ds_read_b128 v[172:175], v156 offset:1024
	ds_read_b128 v[176:179], v156 offset:2048
	ds_read_b128 v[180:183], v156 offset:3072
	v_lshl_add_u64 v[156:157], s[38:39], 0, v[136:137]
	s_add_i32 m0, s58, 0xc000
	ds_read_b128 v[184:187], v147
	ds_read_b128 v[188:191], v147 offset:1024
	ds_read_b128 v[192:195], v147 offset:2048
	ds_read_b128 v[204:207], v147 offset:3072
	ds_read_b128 v[208:211], v147 offset:4096
	ds_read_b128 v[212:215], v147 offset:5120
	ds_read_b128 v[216:219], v147 offset:6144
	ds_read_b128 v[220:223], v147 offset:7168
	global_load_lds_dwordx4 v[156:157], off
	v_lshl_add_u64 v[156:157], s[38:39], 0, v[138:139]
	s_add_i32 m0, s58, 0xe000
	s_nop 0
	global_load_lds_dwordx4 v[156:157], off
	s_waitcnt vmcnt(8)
	s_waitcnt lgkmcnt(0)
	s_barrier
	s_setprio 1
	s_waitcnt lgkmcnt(0)
	v_mfma_f32_16x16x32_bf16 v[128:131], v[140:143], v[184:187], 0
	v_mfma_f32_16x16x32_bf16 v[128:131], v[148:151], v[188:191], v[128:131]
	v_mfma_f32_16x16x32_bf16 v[124:127], v[152:155], v[184:187], 0
	v_mfma_f32_16x16x32_bf16 v[124:127], v[164:167], v[188:191], v[124:127]
	v_mfma_f32_16x16x32_bf16 v[120:123], v[140:143], v[192:195], 0
	v_mfma_f32_16x16x32_bf16 v[120:123], v[148:151], v[204:207], v[120:123]
	v_mfma_f32_16x16x32_bf16 v[112:115], v[152:155], v[192:195], 0
	v_mfma_f32_16x16x32_bf16 v[112:115], v[164:167], v[204:207], v[112:115]
	v_mfma_f32_16x16x32_bf16 v[104:107], v[140:143], v[208:211], 0
	v_mfma_f32_16x16x32_bf16 v[104:107], v[148:151], v[212:215], v[104:107]
	v_mfma_f32_16x16x32_bf16 v[96:99], v[152:155], v[208:211], 0
	v_mfma_f32_16x16x32_bf16 v[96:99], v[164:167], v[212:215], v[96:99]
	v_mfma_f32_16x16x32_bf16 v[88:91], v[140:143], v[216:219], 0
	v_mfma_f32_16x16x32_bf16 v[88:91], v[148:151], v[220:223], v[88:91]
	v_mfma_f32_16x16x32_bf16 v[80:83], v[152:155], v[216:219], 0
	v_mfma_f32_16x16x32_bf16 v[80:83], v[164:167], v[220:223], v[80:83]
	s_setprio 0
	s_setprio 1
	v_mfma_f32_16x16x32_bf16 v[116:119], v[168:171], v[184:187], 0
	v_mfma_f32_16x16x32_bf16 v[116:119], v[172:175], v[188:191], v[116:119]
	v_mfma_f32_16x16x32_bf16 v[108:111], v[176:179], v[184:187], 0
	v_mfma_f32_16x16x32_bf16 v[108:111], v[180:183], v[188:191], v[108:111]
	v_mfma_f32_16x16x32_bf16 v[100:103], v[168:171], v[192:195], 0
	v_mfma_f32_16x16x32_bf16 v[100:103], v[172:175], v[204:207], v[100:103]
	v_mfma_f32_16x16x32_bf16 v[92:95], v[176:179], v[192:195], 0
	v_mfma_f32_16x16x32_bf16 v[92:95], v[180:183], v[204:207], v[92:95]
	v_mfma_f32_16x16x32_bf16 v[84:87], v[168:171], v[208:211], 0
	v_mfma_f32_16x16x32_bf16 v[84:87], v[172:175], v[212:215], v[84:87]
	v_mfma_f32_16x16x32_bf16 v[76:79], v[176:179], v[208:211], 0
	v_mfma_f32_16x16x32_bf16 v[76:79], v[180:183], v[212:215], v[76:79]
	v_mfma_f32_16x16x32_bf16 v[72:75], v[168:171], v[216:219], 0
	v_mfma_f32_16x16x32_bf16 v[72:75], v[172:175], v[220:223], v[72:75]
	s_setprio 2
	s_barrier
	v_mfma_f32_16x16x32_bf16 v[68:71], v[176:179], v[216:219], 0
	v_mfma_f32_16x16x32_bf16 v[68:71], v[180:183], v[220:223], v[68:71]
	s_setprio 0
	s_add_i32 s30, s31, s53
	v_lshl_add_u64 v[156:157], s[40:41], 0, v[2:3]
	s_mov_b32 m0, s30
	ds_read_b128 v[184:187], v147 offset:16384
	ds_read_b128 v[188:191], v147 offset:17408
	ds_read_b128 v[192:195], v147 offset:18432
	ds_read_b128 v[204:207], v147 offset:19456
	ds_read_b128 v[208:211], v147 offset:20480
	ds_read_b128 v[212:215], v147 offset:21504
	ds_read_b128 v[216:219], v147 offset:22528
	ds_read_b128 v[220:223], v147 offset:23552
	global_load_lds_dwordx4 v[156:157], off
	s_add_i32 m0, s30, 0x2000
	s_add_u32 s30, s40, 0x80000
	v_lshl_add_u64 v[196:197], s[40:41], 0, v[0:1]
	s_addc_u32 s31, s41, 0
	s_add_i32 s27, s27, s53
	global_load_lds_dwordx4 v[196:197], off
	v_lshl_add_u64 v[224:225], s[30:31], 0, v[2:3]
	s_mov_b32 m0, s27
	v_lshl_add_u64 v[226:227], s[42:43], 0, v[132:133]
	global_load_lds_dwordx4 v[224:225], off
	v_lshl_add_u64 v[224:225], s[30:31], 0, v[0:1]
	s_add_i32 m0, s27, 0x2000
	s_nop 0
	global_load_lds_dwordx4 v[224:225], off
	v_lshl_add_u64 v[224:225], s[42:43], 0, v[134:135]
	s_mov_b32 m0, s58
	s_nop 0
	global_load_lds_dwordx4 v[224:225], off
	s_mov_b32 m0, s59
	s_nop 0
	global_load_lds_dwordx4 v[226:227], off
	s_waitcnt vmcnt(8)
	s_waitcnt lgkmcnt(0)
	s_barrier
; #define PG8_STAGE(bufoff, gbase, voff) do { _Pragma("unroll") for (int _i = 0; _i < 2; ++_i) \
;         __builtin_amdgcn_global_load_lds((const unsigned*)((const char*)(gbase) + (voff)[_i]), (LAS unsigned*)(lds + (bufoff) + ldsw + _i * 8192), 16, 0, 0); } while (0)
; #define PG8_LDA(dst, b, h) do { _Pragma("unroll") for (int m = 0; m < 4; ++m) _Pragma("unroll") for (int k = 0; k < 2; ++k) dst[m][k] = *(const LAS bf16x8*)(lds + PG8_SA(b, h) + aoff + m * 2048 + k * 1024); } while (0)
; #define PG8_LDB(dst, b, h) do { _Pragma("unroll") for (int n = 0; n < 2; ++n) _Pragma("unroll") for (int k = 0; k < 2; ++k) dst[n][k] = *(const LAS bf16x8*)(lds + PG8_SB(b, h) + boff + n * 2048 + k * 1024); } while (0)
; #define PG8_MMA(ai, bj, At, Bt) do { __builtin_amdgcn_s_setprio(1); _Pragma("unroll") for (int m = 0; m < 4; ++m) _Pragma("unroll") for (int n = 0; n < 2; ++n) _Pragma("unroll") for (int k = 0; k < 2; ++k) \
;         acc[ai][bj][m][n] = __builtin_amdgcn_mfma_f32_16x16x32_bf16(Bt[n][k], At[m][k], acc[ai][bj][m][n], 0, 0, 0); __builtin_amdgcn_s_setprio(0); } while (0)
; #define PG8_WAIT_V(n) asm volatile("s_waitcnt vmcnt(" #n ")" ::: "memory")
; #define PG8_WAIT_L(n) asm volatile("s_waitcnt lgkmcnt(" #n ")" ::: "memory")
; #define PG8_BAR __builtin_amdgcn_s_barrier()
; #define PG8_SCHED __builtin_amdgcn_sched_barrier(0)
; template <class Epi, class Sched, bool ALIGN_EPI = true>
; __device__ __forceinline__ void gemm_phase(LAS unsigned char* lds, const Gemm g, const Sched& S, const Epi& E) {
;     ...
;             PG8_WAIT_V(8); PG8_WAIT_L(0); PG8_BAR; PG8_MMA(1, 0, At, B0); PG8_MMA(1, 1, At, B1); PG8_BAR; PG8_SCHED;
;             PG8_LDB(B0, 1, 0); PG8_LDB(B1, 1, 1); PG8_SCHED; PG8_LDA(At, 1, 0); PG8_STAGE(PG8_SA(0, 1), a2 + hA, voffA);
;             PG8_WAIT_V(8); PG8_WAIT_L(0); PG8_BAR; PG8_MMA(0, 0, At, B0); PG8_MMA(0, 1, At, B1); PG8_BAR; PG8_SCHED;
;             PG8_LDA(At, 1, 1); PG8_STAGE(PG8_SB(1, 0), b3, voffB); PG8_STAGE(PG8_SB(1, 1), b3 + hB, voffB); PG8_STAGE(PG8_SA(1, 0), a3, voffA);
;             PG8_WAIT_V(8); PG8_WAIT_L(0); PG8_BAR; PG8_MMA(1, 0, At, B0); PG8_MMA(1, 1, At, B1); PG8_BAR; PG8_SCHED;
	s_setprio 1
	s_waitcnt lgkmcnt(0)
	v_mfma_f32_16x16x32_bf16 v[64:67], v[140:143], v[184:187], 0
	v_mfma_f32_16x16x32_bf16 v[64:67], v[148:151], v[188:191], v[64:67]
	v_mfma_f32_16x16x32_bf16 v[60:63], v[152:155], v[184:187], 0
	v_mfma_f32_16x16x32_bf16 v[60:63], v[164:167], v[188:191], v[60:63]
	v_mfma_f32_16x16x32_bf16 v[56:59], v[140:143], v[192:195], 0
	v_mfma_f32_16x16x32_bf16 v[56:59], v[148:151], v[204:207], v[56:59]
	v_mfma_f32_16x16x32_bf16 v[48:51], v[152:155], v[192:195], 0
	v_mfma_f32_16x16x32_bf16 v[48:51], v[164:167], v[204:207], v[48:51]
	v_mfma_f32_16x16x32_bf16 v[40:43], v[140:143], v[208:211], 0
	v_mfma_f32_16x16x32_bf16 v[40:43], v[148:151], v[212:215], v[40:43]
	v_mfma_f32_16x16x32_bf16 v[32:35], v[152:155], v[208:211], 0
	v_mfma_f32_16x16x32_bf16 v[32:35], v[164:167], v[212:215], v[32:35]
	v_mfma_f32_16x16x32_bf16 v[24:27], v[140:143], v[216:219], 0
	v_mfma_f32_16x16x32_bf16 v[24:27], v[148:151], v[220:223], v[24:27]
	v_mfma_f32_16x16x32_bf16 v[16:19], v[152:155], v[216:219], 0
	v_mfma_f32_16x16x32_bf16 v[16:19], v[164:167], v[220:223], v[16:19]
	s_setprio 0
	s_setprio 1
	v_mfma_f32_16x16x32_bf16 v[52:55], v[168:171], v[184:187], 0
	v_mfma_f32_16x16x32_bf16 v[52:55], v[172:175], v[188:191], v[52:55]
	v_mfma_f32_16x16x32_bf16 v[44:47], v[176:179], v[184:187], 0
	v_mfma_f32_16x16x32_bf16 v[44:47], v[180:183], v[188:191], v[44:47]
	v_mfma_f32_16x16x32_bf16 v[36:39], v[168:171], v[192:195], 0
	v_mfma_f32_16x16x32_bf16 v[36:39], v[172:175], v[204:207], v[36:39]
	v_mfma_f32_16x16x32_bf16 v[28:31], v[176:179], v[192:195], 0
	v_mfma_f32_16x16x32_bf16 v[28:31], v[180:183], v[204:207], v[28:31]
	v_mfma_f32_16x16x32_bf16 v[20:23], v[168:171], v[208:211], 0
	v_mfma_f32_16x16x32_bf16 v[20:23], v[172:175], v[212:215], v[20:23]
	v_mfma_f32_16x16x32_bf16 v[12:15], v[176:179], v[208:211], 0
	v_mfma_f32_16x16x32_bf16 v[12:15], v[180:183], v[212:215], v[12:15]
	v_mfma_f32_16x16x32_bf16 v[8:11], v[168:171], v[216:219], 0
	v_mfma_f32_16x16x32_bf16 v[8:11], v[172:175], v[220:223], v[8:11]
	s_setprio 2
	s_barrier
	v_mfma_f32_16x16x32_bf16 v[4:7], v[176:179], v[216:219], 0
	v_mfma_f32_16x16x32_bf16 v[4:7], v[180:183], v[220:223], v[4:7]
	s_setprio 0
	s_add_i32 s27, 0, 0x18000
	v_add_u32_e32 v158, s27, v145
	s_add_i32 s65, 0, 0x1c000
	ds_read_b128 v[140:143], v158
	ds_read_b128 v[148:151], v158 offset:1024
	ds_read_b128 v[152:155], v158 offset:2048
	ds_read_b128 v[164:167], v158 offset:3072
	v_add_u32_e32 v158, s65, v145
	ds_read_b128 v[168:171], v158
	ds_read_b128 v[172:175], v158 offset:1024
	ds_read_b128 v[176:179], v158 offset:2048
	ds_read_b128 v[180:183], v158 offset:3072
	s_add_u32 s30, s42, 0x80000
	s_addc_u32 s31, s43, 0
	s_mov_b32 m0, s60
	v_lshl_add_u64 v[228:229], s[30:31], 0, v[134:135]
	ds_read_b128 v[184:187], v147 offset:32768
	ds_read_b128 v[188:191], v147 offset:33792
	ds_read_b128 v[192:195], v147 offset:34816
	ds_read_b128 v[204:207], v147 offset:35840
	ds_read_b128 v[208:211], v147 offset:36864
	ds_read_b128 v[212:215], v147 offset:37888
	ds_read_b128 v[216:219], v147 offset:38912
	ds_read_b128 v[220:223], v147 offset:39936
	global_load_lds_dwordx4 v[228:229], off
	v_lshl_add_u64 v[228:229], s[30:31], 0, v[132:133]
	s_mov_b32 m0, s61
	s_nop 0
	global_load_lds_dwordx4 v[228:229], off
	s_waitcnt vmcnt(8)
	s_waitcnt lgkmcnt(0)
	s_barrier
	s_setprio 1
	s_waitcnt lgkmcnt(0)
	v_mfma_f32_16x16x32_bf16 v[128:131], v[140:143], v[184:187], v[128:131]
	v_mfma_f32_16x16x32_bf16 v[128:131], v[148:151], v[188:191], v[128:131]
	v_mfma_f32_16x16x32_bf16 v[124:127], v[152:155], v[184:187], v[124:127]
	v_mfma_f32_16x16x32_bf16 v[124:127], v[164:167], v[188:191], v[124:127]
	v_mfma_f32_16x16x32_bf16 v[120:123], v[140:143], v[192:195], v[120:123]
	v_mfma_f32_16x16x32_bf16 v[120:123], v[148:151], v[204:207], v[120:123]
	v_mfma_f32_16x16x32_bf16 v[112:115], v[152:155], v[192:195], v[112:115]
	v_mfma_f32_16x16x32_bf16 v[112:115], v[164:167], v[204:207], v[112:115]
	v_mfma_f32_16x16x32_bf16 v[104:107], v[140:143], v[208:211], v[104:107]
	v_mfma_f32_16x16x32_bf16 v[104:107], v[148:151], v[212:215], v[104:107]
	v_mfma_f32_16x16x32_bf16 v[96:99], v[152:155], v[208:211], v[96:99]
	v_mfma_f32_16x16x32_bf16 v[96:99], v[164:167], v[212:215], v[96:99]
	v_mfma_f32_16x16x32_bf16 v[88:91], v[140:143], v[216:219], v[88:91]
	v_mfma_f32_16x16x32_bf16 v[88:91], v[148:151], v[220:223], v[88:91]
	v_mfma_f32_16x16x32_bf16 v[80:83], v[152:155], v[216:219], v[80:83]
	v_mfma_f32_16x16x32_bf16 v[80:83], v[164:167], v[220:223], v[80:83]
	s_setprio 0
	s_setprio 1
	v_mfma_f32_16x16x32_bf16 v[116:119], v[168:171], v[184:187], v[116:119]
	v_mfma_f32_16x16x32_bf16 v[116:119], v[172:175], v[188:191], v[116:119]
	v_mfma_f32_16x16x32_bf16 v[108:111], v[176:179], v[184:187], v[108:111]
	v_mfma_f32_16x16x32_bf16 v[108:111], v[180:183], v[188:191], v[108:111]
	v_mfma_f32_16x16x32_bf16 v[100:103], v[168:171], v[192:195], v[100:103]
	v_mfma_f32_16x16x32_bf16 v[100:103], v[172:175], v[204:207], v[100:103]
	v_mfma_f32_16x16x32_bf16 v[92:95], v[176:179], v[192:195], v[92:95]
	v_mfma_f32_16x16x32_bf16 v[92:95], v[180:183], v[204:207], v[92:95]
	v_mfma_f32_16x16x32_bf16 v[84:87], v[168:171], v[208:211], v[84:87]
	v_mfma_f32_16x16x32_bf16 v[84:87], v[172:175], v[212:215], v[84:87]
	v_mfma_f32_16x16x32_bf16 v[76:79], v[176:179], v[208:211], v[76:79]
	v_mfma_f32_16x16x32_bf16 v[76:79], v[180:183], v[212:215], v[76:79]
	v_mfma_f32_16x16x32_bf16 v[72:75], v[168:171], v[216:219], v[72:75]
	v_mfma_f32_16x16x32_bf16 v[72:75], v[172:175], v[220:223], v[72:75]
	s_setprio 2
	s_barrier
; #define PG8_STAGE(bufoff, gbase, voff) do { _Pragma("unroll") for (int _i = 0; _i < 2; ++_i) \
;         __builtin_amdgcn_global_load_lds((const unsigned*)((const char*)(gbase) + (voff)[_i]), (LAS unsigned*)(lds + (bufoff) + ldsw + _i * 8192), 16, 0, 0); } while (0)
; #define PG8_LDA(dst, b, h) do { _Pragma("unroll") for (int m = 0; m < 4; ++m) _Pragma("unroll") for (int k = 0; k < 2; ++k) dst[m][k] = *(const LAS bf16x8*)(lds + PG8_SA(b, h) + aoff + m * 2048 + k * 1024); } while (0)
; #define PG8_LDB(dst, b, h) do { _Pragma("unroll") for (int n = 0; n < 2; ++n) _Pragma("unroll") for (int k = 0; k < 2; ++k) dst[n][k] = *(const LAS bf16x8*)(lds + PG8_SB(b, h) + boff + n * 2048 + k * 1024); } while (0)
; #define PG8_WAIT_V(n) asm volatile("s_waitcnt vmcnt(" #n ")" ::: "memory")
; #define PG8_WAIT_L(n) asm volatile("s_waitcnt lgkmcnt(" #n ")" ::: "memory")
; #define PG8_BAR __builtin_amdgcn_s_barrier()
; #define PG8_SCHED __builtin_amdgcn_sched_barrier(0)
; template <class Epi, class Sched, bool ALIGN_EPI = true>
; __device__ __forceinline__ void gemm_phase(LAS unsigned char* lds, const Gemm g, const Sched& S, const Epi& E) {
;     ...
;             const char* a2 = last ? nA : cA + (size_t)(t + 2) * kstep; const char* b2 = last ? nB : cB + (size_t)(t + 2) * kstep;
;             const char* a3 = a2 + kstep; const char* b3 = b2 + kstep;
;             PG8_LDB(B0, 0, 0); PG8_LDB(B1, 0, 1); PG8_SCHED; PG8_LDA(At, 0, 0); PG8_STAGE(PG8_SA(1, 1), a1 + hA, voffA);
;             PG8_WAIT_V(8); PG8_WAIT_L(0); PG8_BAR; PG8_MMA(0, 0, At, B0); PG8_MMA(0, 1, At, B1); PG8_BAR; PG8_SCHED;
;             PG8_LDA(At, 0, 1); PG8_STAGE(PG8_SB(0, 0), b2, voffB); PG8_STAGE(PG8_SB(0, 1), b2 + hB, voffB); PG8_STAGE(PG8_SA(0, 0), a2, voffA);
;             PG8_WAIT_V(8); PG8_WAIT_L(0); PG8_BAR; PG8_MMA(1, 0, At, B0); PG8_MMA(1, 1, At, B1); PG8_BAR; PG8_SCHED;
;             PG8_LDB(B0, 1, 0); PG8_LDB(B1, 1, 1); PG8_SCHED; PG8_LDA(At, 1, 0); PG8_STAGE(PG8_SA(0, 1), a2 + hA, voffA);
;             PG8_WAIT_V(8); PG8_WAIT_L(0); PG8_BAR; PG8_MMA(0, 0, At, B0); PG8_MMA(0, 1, At, B1); PG8_BAR; PG8_SCHED;
;             PG8_LDA(At, 1, 1); PG8_STAGE(PG8_SB(1, 0), b3, voffB); PG8_STAGE(PG8_SB(1, 1), b3 + hB, voffB); PG8_STAGE(PG8_SA(1, 0), a3, voffA);
;             PG8_WAIT_V(8); PG8_WAIT_L(0); PG8_BAR; PG8_MMA(1, 0, At, B0); PG8_MMA(1, 1, At, B1); PG8_BAR; PG8_SCHED;
	v_mfma_f32_16x16x32_bf16 v[68:71], v[176:179], v[216:219], v[68:71]
	v_mfma_f32_16x16x32_bf16 v[68:71], v[180:183], v[220:223], v[68:71]
	s_setprio 0
	s_add_i32 s27, s27, s53
	v_lshl_add_u64 v[156:157], v[156:157], 0, s[86:87]
	s_mov_b32 m0, s27
	ds_read_b128 v[184:187], v147 offset:49152
	ds_read_b128 v[188:191], v147 offset:50176
	ds_read_b128 v[192:195], v147 offset:51200
	ds_read_b128 v[204:207], v147 offset:52224
	ds_read_b128 v[208:211], v147 offset:53248
	ds_read_b128 v[212:215], v147 offset:54272
	ds_read_b128 v[216:219], v147 offset:55296
	ds_read_b128 v[220:223], v147 offset:56320
	global_load_lds_dwordx4 v[156:157], off
	s_add_i32 m0, s27, 0x2000
	s_add_u32 s30, s40, 0x80080
	v_lshl_add_u64 v[156:157], v[196:197], 0, s[86:87]
	s_addc_u32 s31, s41, 0
	s_add_i32 s27, s65, s53
	global_load_lds_dwordx4 v[156:157], off
	v_lshl_add_u64 v[156:157], s[30:31], 0, v[2:3]
	s_mov_b32 m0, s27
	s_nop 0
	global_load_lds_dwordx4 v[156:157], off
	v_lshl_add_u64 v[156:157], s[30:31], 0, v[0:1]
	s_add_i32 m0, s27, 0x2000
	s_nop 0
	global_load_lds_dwordx4 v[156:157], off
	v_lshl_add_u64 v[156:157], v[224:225], 0, s[86:87]
	s_mov_b32 m0, s62
	s_nop 0
	global_load_lds_dwordx4 v[156:157], off
	v_lshl_add_u64 v[156:157], v[226:227], 0, s[86:87]
	s_mov_b32 m0, s63
	s_nop 0
	global_load_lds_dwordx4 v[156:157], off
	s_waitcnt vmcnt(8)
	s_waitcnt lgkmcnt(0)
	s_barrier
	s_setprio 1
	s_waitcnt lgkmcnt(0)
	v_mfma_f32_16x16x32_bf16 v[64:67], v[140:143], v[184:187], v[64:67]
	v_mfma_f32_16x16x32_bf16 v[64:67], v[148:151], v[188:191], v[64:67]
	s_add_i32 s26, s26, 2
	s_add_u32 s38, s38, 0x100
	v_mfma_f32_16x16x32_bf16 v[60:63], v[152:155], v[184:187], v[60:63]
	v_mfma_f32_16x16x32_bf16 v[60:63], v[164:167], v[188:191], v[60:63]
	s_addc_u32 s39, s39, 0
	s_add_u32 s24, s24, 0x100
	v_mfma_f32_16x16x32_bf16 v[56:59], v[140:143], v[192:195], v[56:59]
	v_mfma_f32_16x16x32_bf16 v[56:59], v[148:151], v[204:207], v[56:59]
	s_addc_u32 s25, s25, 0
	s_add_u32 s27, s38, 0xfff80080
	v_mfma_f32_16x16x32_bf16 v[48:51], v[152:155], v[192:195], v[48:51]
	v_mfma_f32_16x16x32_bf16 v[48:51], v[164:167], v[204:207], v[48:51]
	s_addc_u32 s30, s39, -1
	s_add_i32 s31, 0, 0x10000
	v_mfma_f32_16x16x32_bf16 v[40:43], v[140:143], v[208:211], v[40:43]
	v_mfma_f32_16x16x32_bf16 v[40:43], v[148:151], v[212:215], v[40:43]
	s_cmp_eq_u32 s26, 28
	s_cselect_b32 s43, s11, s30
	v_mfma_f32_16x16x32_bf16 v[32:35], v[152:155], v[208:211], v[32:35]
	v_mfma_f32_16x16x32_bf16 v[32:35], v[164:167], v[212:215], v[32:35]
	s_cselect_b32 s42, s18, s27
	s_cselect_b32 s41, s9, s25
	v_mfma_f32_16x16x32_bf16 v[24:27], v[140:143], v[216:219], v[24:27]
	v_mfma_f32_16x16x32_bf16 v[24:27], v[148:151], v[220:223], v[24:27]
	s_cselect_b32 s40, s19, s24
	s_add_i32 s27, 0, 0x14000
	v_mfma_f32_16x16x32_bf16 v[16:19], v[152:155], v[216:219], v[16:19]
	v_mfma_f32_16x16x32_bf16 v[16:19], v[164:167], v[220:223], v[16:19]
	s_setprio 0
	s_setprio 1
	v_mfma_f32_16x16x32_bf16 v[52:55], v[168:171], v[184:187], v[52:55]
	v_mfma_f32_16x16x32_bf16 v[52:55], v[172:175], v[188:191], v[52:55]
	v_mfma_f32_16x16x32_bf16 v[44:47], v[176:179], v[184:187], v[44:47]
	v_mfma_f32_16x16x32_bf16 v[44:47], v[180:183], v[188:191], v[44:47]
	v_mfma_f32_16x16x32_bf16 v[36:39], v[168:171], v[192:195], v[36:39]
	v_mfma_f32_16x16x32_bf16 v[36:39], v[172:175], v[204:207], v[36:39]
	v_mfma_f32_16x16x32_bf16 v[28:31], v[176:179], v[192:195], v[28:31]
	v_mfma_f32_16x16x32_bf16 v[28:31], v[180:183], v[204:207], v[28:31]
	v_mfma_f32_16x16x32_bf16 v[20:23], v[168:171], v[208:211], v[20:23]
	v_mfma_f32_16x16x32_bf16 v[20:23], v[172:175], v[212:215], v[20:23]
	v_mfma_f32_16x16x32_bf16 v[12:15], v[176:179], v[208:211], v[12:15]
	v_mfma_f32_16x16x32_bf16 v[12:15], v[180:183], v[212:215], v[12:15]
	v_mfma_f32_16x16x32_bf16 v[8:11], v[168:171], v[216:219], v[8:11]
	v_mfma_f32_16x16x32_bf16 v[8:11], v[172:175], v[220:223], v[8:11]
	s_setprio 2
	s_barrier
	v_mfma_f32_16x16x32_bf16 v[4:7], v[176:179], v[216:219], v[4:7]
	v_mfma_f32_16x16x32_bf16 v[4:7], v[180:183], v[220:223], v[4:7]
	s_setprio 0
	s_cmp_gt_u32 s26, 29
	s_cbranch_scc1 .Lpeel_exit_218
	.p2align	6

;     __device__ bool next(int i, Unit& u) const { if (i >= 2) return false; const int x = c & 7, j = c >> 3; u.pm = 32 * i + 4 * x + (j & 3); u.pn = j >> 2; return true; }
; #define PG8_STAGE(bufoff, gbase, voff) do { _Pragma("unroll") for (int _i = 0; _i < 2; ++_i) \
;         __builtin_amdgcn_global_load_lds((const unsigned*)((const char*)(gbase) + (voff)[_i]), (LAS unsigned*)(lds + (bufoff) + ldsw + _i * 8192), 16, 0, 0); } while (0)
; #define PG8_LDA(dst, b, h) do { _Pragma("unroll") for (int m = 0; m < 4; ++m) _Pragma("unroll") for (int k = 0; k < 2; ++k) dst[m][k] = *(const LAS bf16x8*)(lds + PG8_SA(b, h) + aoff + m * 2048 + k * 1024); } while (0)
; #define PG8_LDB(dst, b, h) do { _Pragma("unroll") for (int n = 0; n < 2; ++n) _Pragma("unroll") for (int k = 0; k < 2; ++k) dst[n][k] = *(const LAS bf16x8*)(lds + PG8_SB(b, h) + boff + n * 2048 + k * 1024); } while (0)
; #define PG8_WAIT_V(n) asm volatile("s_waitcnt vmcnt(" #n ")" ::: "memory")
; #define PG8_WAIT_L(n) asm volatile("s_waitcnt lgkmcnt(" #n ")" ::: "memory")
; #define PG8_BAR __builtin_amdgcn_s_barrier()
; template <class Epi, class Sched, bool ALIGN_EPI = true>
; __device__ __forceinline__ void gemm_phase(LAS unsigned char* lds, const Gemm g, const Sched& S, const Epi& E) {
;     ...
;         const bool has_next = S.next(ui + 1, nxt);
;         const char* nA = has_next ? (const char*)g.A + ((size_t)nxt.pm * BM * g.lda + (size_t)nxt.pn * g.a_pn_off) * 2 : cA; const char* nB = has_next ? (const char*)g.Bt + (size_t)nxt.pn * BM * g.ldb * 2 : cB;
;         for (int t = 0; t < nt; t += 2) {
;             const bool last = (t == nt - 2);
;             const char* a1 = cA + (size_t)(t + 1) * kstep;
;             const char* a2 = last ? nA : cA + (size_t)(t + 2) * kstep; const char* b2 = last ? nB : cB + (size_t)(t + 2) * kstep;
;             const char* a3 = a2 + kstep; const char* b3 = b2 + kstep;
;             PG8_LDB(B0, 0, 0); PG8_LDB(B1, 0, 1); PG8_SCHED; PG8_LDA(At, 0, 0); PG8_STAGE(PG8_SA(1, 1), a1 + hA, voffA);
;             PG8_WAIT_V(8); PG8_WAIT_L(0); PG8_BAR; PG8_MMA(0, 0, At, B0); PG8_MMA(0, 1, At, B1); PG8_BAR; PG8_SCHED;
;             PG8_LDA(At, 0, 1); PG8_STAGE(PG8_SB(0, 0), b2, voffB); PG8_STAGE(PG8_SB(0, 1), b2 + hB, voffB); PG8_STAGE(PG8_SA(0, 0), a2, voffA);
;             PG8_WAIT_V(8); PG8_WAIT_L(0); PG8_BAR; PG8_MMA(1, 0, At, B0); PG8_MMA(1, 1, At, B1); PG8_BAR; PG8_SCHED;
.LBB0_666:
	s_mov_b32 s82, s81
	s_or_b32 s81, s17, s68
	s_mov_b64 s[10:11], s[12:13]
	s_lshl_b32 s12, s81, 20
	s_add_u32 s12, s28, s12
	s_addc_u32 s13, s29, 0
	s_and_b64 s[16:17], s[38:39], exec
	s_cselect_b32 s16, s13, s11
	s_cselect_b32 s17, s12, s10
	s_add_u32 s18, s10, 0x100
	s_addc_u32 s19, s11, 0
	s_add_u32 s10, s10, 0x80080
	s_addc_u32 s11, s11, 0
	v_lshl_add_u64 v[132:133], s[10:11], 0, v[166:167]
	v_lshl_add_u64 v[134:135], s[10:11], 0, v[168:169]
	s_mov_b32 s24, -2
	s_mov_b64 s[10:11], 0
	s_add_u32 vcc_lo, s10, 0x100
	s_addc_u32 vcc_hi, s11, 0
	s_add_u32 s25, s18, s10
	s_addc_u32 s26, s19, s11
	s_add_i32 s27, 0, 0x10000
	s_cmp_eq_u32 s24, 28
	s_cselect_b32 s65, s16, s26
	s_cselect_b32 s26, 0, vcc_lo
	s_cselect_b32 s64, s17, s25
	s_cselect_b32 s25, 0, vcc_hi
	s_add_u32 s62, s14, s26
	v_add_u32_e32 v160, s27, v186
	s_addc_u32 s63, s15, s25
	s_add_i32 s25, 0, 0x14000
	ds_read_b128 v[136:139], v160
	ds_read_b128 v[140:143], v160 offset:1024
	ds_read_b128 v[144:147], v160 offset:2048
	ds_read_b128 v[170:173], v160 offset:3072
	v_add_u32_e32 v160, s25, v186
	ds_read_b128 v[174:177], v160
	ds_read_b128 v[178:181], v160 offset:1024
	ds_read_b128 v[182:185], v160 offset:2048
	ds_read_b128 v[208:211], v160 offset:3072
	v_lshl_add_u64 v[244:245], v[132:133], 0, s[10:11]
	s_add_i32 m0, s53, 0xc000
	ds_read_b128 v[212:215], v197
	ds_read_b128 v[216:219], v197 offset:1024
	ds_read_b128 v[220:223], v197 offset:2048
	ds_read_b128 v[224:227], v197 offset:3072
	ds_read_b128 v[228:231], v197 offset:4096
	ds_read_b128 v[232:235], v197 offset:5120
	ds_read_b128 v[236:239], v197 offset:6144
	ds_read_b128 v[240:243], v197 offset:7168
	global_load_lds_dwordx4 v[244:245], off
	v_lshl_add_u64 v[244:245], v[134:135], 0, s[10:11]
	s_add_i32 m0, s53, 0xe000
	s_nop 0
	global_load_lds_dwordx4 v[244:245], off
	s_waitcnt vmcnt(8)
	s_waitcnt lgkmcnt(0)
	s_barrier
	s_setprio 1
	s_waitcnt lgkmcnt(0)
	v_mfma_f32_16x16x32_bf16 v[36:39], v[136:139], v[212:215], 0
	v_mfma_f32_16x16x32_bf16 v[36:39], v[140:143], v[216:219], v[36:39]
	v_mfma_f32_16x16x32_bf16 v[40:43], v[144:147], v[212:215], 0
	v_mfma_f32_16x16x32_bf16 v[40:43], v[170:173], v[216:219], v[40:43]
	v_mfma_f32_16x16x32_bf16 v[68:71], v[136:139], v[220:223], 0
	v_mfma_f32_16x16x32_bf16 v[68:71], v[140:143], v[224:227], v[68:71]
	v_mfma_f32_16x16x32_bf16 v[72:75], v[144:147], v[220:223], 0
	v_mfma_f32_16x16x32_bf16 v[72:75], v[170:173], v[224:227], v[72:75]
	v_mfma_f32_16x16x32_bf16 v[100:103], v[136:139], v[228:231], 0
	v_mfma_f32_16x16x32_bf16 v[100:103], v[140:143], v[232:235], v[100:103]
	v_mfma_f32_16x16x32_bf16 v[104:107], v[144:147], v[228:231], 0
	v_mfma_f32_16x16x32_bf16 v[104:107], v[170:173], v[232:235], v[104:107]
	v_mfma_f32_16x16x32_bf16 v[128:131], v[136:139], v[236:239], 0
	v_mfma_f32_16x16x32_bf16 v[128:131], v[140:143], v[240:243], v[128:131]
	v_mfma_f32_16x16x32_bf16 v[124:127], v[144:147], v[236:239], 0
	v_mfma_f32_16x16x32_bf16 v[124:127], v[170:173], v[240:243], v[124:127]
	s_setprio 0
	s_setprio 1
	v_mfma_f32_16x16x32_bf16 v[8:11], v[174:177], v[212:215], 0
	v_mfma_f32_16x16x32_bf16 v[8:11], v[178:181], v[216:219], v[8:11]
	v_mfma_f32_16x16x32_bf16 v[4:7], v[182:185], v[212:215], 0
	v_mfma_f32_16x16x32_bf16 v[4:7], v[208:211], v[216:219], v[4:7]
	v_mfma_f32_16x16x32_bf16 v[32:35], v[174:177], v[220:223], 0
	v_mfma_f32_16x16x32_bf16 v[32:35], v[178:181], v[224:227], v[32:35]
	v_mfma_f32_16x16x32_bf16 v[28:31], v[182:185], v[220:223], 0
	v_mfma_f32_16x16x32_bf16 v[28:31], v[208:211], v[224:227], v[28:31]
	v_mfma_f32_16x16x32_bf16 v[56:59], v[174:177], v[228:231], 0
	v_mfma_f32_16x16x32_bf16 v[56:59], v[178:181], v[232:235], v[56:59]
	v_mfma_f32_16x16x32_bf16 v[52:55], v[182:185], v[228:231], 0
	v_mfma_f32_16x16x32_bf16 v[52:55], v[208:211], v[232:235], v[52:55]
	v_mfma_f32_16x16x32_bf16 v[80:83], v[174:177], v[236:239], 0
	v_mfma_f32_16x16x32_bf16 v[80:83], v[178:181], v[240:243], v[80:83]
	s_setprio 2
	s_barrier
	v_mfma_f32_16x16x32_bf16 v[76:79], v[182:185], v[236:239], 0
	v_mfma_f32_16x16x32_bf16 v[76:79], v[208:211], v[240:243], v[76:79]
	s_setprio 0
	s_add_i32 s10, s27, s67
	v_lshl_add_u64 v[244:245], s[62:63], 0, v[2:3]
	s_mov_b32 m0, s10
	ds_read_b128 v[212:215], v197 offset:16384
	ds_read_b128 v[216:219], v197 offset:17408
	ds_read_b128 v[220:223], v197 offset:18432
	ds_read_b128 v[224:227], v197 offset:19456
	ds_read_b128 v[228:231], v197 offset:20480
	ds_read_b128 v[232:235], v197 offset:21504
	ds_read_b128 v[236:239], v197 offset:22528
	ds_read_b128 v[240:243], v197 offset:23552
	global_load_lds_dwordx4 v[244:245], off
	s_add_i32 m0, s10, 0x2000
	s_add_u32 s10, s62, 0x80000
	v_lshl_add_u64 v[246:247], s[62:63], 0, v[150:151]
	s_addc_u32 s11, s63, 0
	s_add_i32 s25, s25, s67
	global_load_lds_dwordx4 v[246:247], off
	v_lshl_add_u64 v[248:249], s[10:11], 0, v[2:3]
	s_mov_b32 m0, s25
	v_lshl_add_u64 v[160:161], s[64:65], 0, v[148:149]
	global_load_lds_dwordx4 v[248:249], off
	v_lshl_add_u64 v[248:249], s[10:11], 0, v[150:151]
	s_add_i32 m0, s25, 0x2000
	s_nop 0
	global_load_lds_dwordx4 v[248:249], off
	v_lshl_add_u64 v[248:249], s[64:65], 0, v[0:1]
	s_mov_b32 m0, s53
	s_nop 0
	global_load_lds_dwordx4 v[248:249], off
	s_mov_b32 m0, s66
	s_nop 0
	global_load_lds_dwordx4 v[160:161], off
	s_waitcnt vmcnt(8)
	s_waitcnt lgkmcnt(0)
	s_barrier
; #define PG8_STAGE(bufoff, gbase, voff) do { _Pragma("unroll") for (int _i = 0; _i < 2; ++_i) \
;         __builtin_amdgcn_global_load_lds((const unsigned*)((const char*)(gbase) + (voff)[_i]), (LAS unsigned*)(lds + (bufoff) + ldsw + _i * 8192), 16, 0, 0); } while (0)
; #define PG8_LDA(dst, b, h) do { _Pragma("unroll") for (int m = 0; m < 4; ++m) _Pragma("unroll") for (int k = 0; k < 2; ++k) dst[m][k] = *(const LAS bf16x8*)(lds + PG8_SA(b, h) + aoff + m * 2048 + k * 1024); } while (0)
; #define PG8_LDB(dst, b, h) do { _Pragma("unroll") for (int n = 0; n < 2; ++n) _Pragma("unroll") for (int k = 0; k < 2; ++k) dst[n][k] = *(const LAS bf16x8*)(lds + PG8_SB(b, h) + boff + n * 2048 + k * 1024); } while (0)
; #define PG8_MMA(ai, bj, At, Bt) do { __builtin_amdgcn_s_setprio(1); _Pragma("unroll") for (int m = 0; m < 4; ++m) _Pragma("unroll") for (int n = 0; n < 2; ++n) _Pragma("unroll") for (int k = 0; k < 2; ++k) \
;         acc[ai][bj][m][n] = __builtin_amdgcn_mfma_f32_16x16x32_bf16(Bt[n][k], At[m][k], acc[ai][bj][m][n], 0, 0, 0); __builtin_amdgcn_s_setprio(0); } while (0)
; #define PG8_WAIT_V(n) asm volatile("s_waitcnt vmcnt(" #n ")" ::: "memory")
; #define PG8_WAIT_L(n) asm volatile("s_waitcnt lgkmcnt(" #n ")" ::: "memory")
; #define PG8_BAR __builtin_amdgcn_s_barrier()
; #define PG8_SCHED __builtin_amdgcn_sched_barrier(0)
; template <class Epi, class Sched, bool ALIGN_EPI = true>
; __device__ __forceinline__ void gemm_phase(LAS unsigned char* lds, const Gemm g, const Sched& S, const Epi& E) {
;     ...
;             PG8_WAIT_V(8); PG8_WAIT_L(0); PG8_BAR; PG8_MMA(1, 0, At, B0); PG8_MMA(1, 1, At, B1); PG8_BAR; PG8_SCHED;
;             PG8_LDB(B0, 1, 0); PG8_LDB(B1, 1, 1); PG8_SCHED; PG8_LDA(At, 1, 0); PG8_STAGE(PG8_SA(0, 1), a2 + hA, voffA);
;             PG8_WAIT_V(8); PG8_WAIT_L(0); PG8_BAR; PG8_MMA(0, 0, At, B0); PG8_MMA(0, 1, At, B1); PG8_BAR; PG8_SCHED;
;             PG8_LDA(At, 1, 1); PG8_STAGE(PG8_SB(1, 0), b3, voffB); PG8_STAGE(PG8_SB(1, 1), b3 + hB, voffB); PG8_STAGE(PG8_SA(1, 0), a3, voffA);
;             PG8_WAIT_V(8); PG8_WAIT_L(0); PG8_BAR; PG8_MMA(1, 0, At, B0); PG8_MMA(1, 1, At, B1); PG8_BAR; PG8_SCHED;
	s_setprio 1
	s_waitcnt lgkmcnt(0)
	v_mfma_f32_16x16x32_bf16 v[120:123], v[136:139], v[212:215], 0
	v_mfma_f32_16x16x32_bf16 v[120:123], v[140:143], v[216:219], v[120:123]
	v_mfma_f32_16x16x32_bf16 v[116:119], v[144:147], v[212:215], 0
	v_mfma_f32_16x16x32_bf16 v[116:119], v[170:173], v[216:219], v[116:119]
	v_mfma_f32_16x16x32_bf16 v[96:99], v[136:139], v[220:223], 0
	v_mfma_f32_16x16x32_bf16 v[96:99], v[140:143], v[224:227], v[96:99]
	v_mfma_f32_16x16x32_bf16 v[92:95], v[144:147], v[220:223], 0
	v_mfma_f32_16x16x32_bf16 v[92:95], v[170:173], v[224:227], v[92:95]
	v_mfma_f32_16x16x32_bf16 v[64:67], v[136:139], v[228:231], 0
	v_mfma_f32_16x16x32_bf16 v[64:67], v[140:143], v[232:235], v[64:67]
	v_mfma_f32_16x16x32_bf16 v[60:63], v[144:147], v[228:231], 0
	v_mfma_f32_16x16x32_bf16 v[60:63], v[170:173], v[232:235], v[60:63]
	v_mfma_f32_16x16x32_bf16 v[24:27], v[136:139], v[236:239], 0
	v_mfma_f32_16x16x32_bf16 v[24:27], v[140:143], v[240:243], v[24:27]
	v_mfma_f32_16x16x32_bf16 v[20:23], v[144:147], v[236:239], 0
	v_mfma_f32_16x16x32_bf16 v[20:23], v[170:173], v[240:243], v[20:23]
	s_setprio 0
	s_setprio 1
	v_mfma_f32_16x16x32_bf16 v[112:115], v[174:177], v[212:215], 0
	v_mfma_f32_16x16x32_bf16 v[112:115], v[178:181], v[216:219], v[112:115]
	v_mfma_f32_16x16x32_bf16 v[108:111], v[182:185], v[212:215], 0
	v_mfma_f32_16x16x32_bf16 v[108:111], v[208:211], v[216:219], v[108:111]
	v_mfma_f32_16x16x32_bf16 v[88:91], v[174:177], v[220:223], 0
	v_mfma_f32_16x16x32_bf16 v[88:91], v[178:181], v[224:227], v[88:91]
	v_mfma_f32_16x16x32_bf16 v[84:87], v[182:185], v[220:223], 0
	v_mfma_f32_16x16x32_bf16 v[84:87], v[208:211], v[224:227], v[84:87]
	v_mfma_f32_16x16x32_bf16 v[48:51], v[174:177], v[228:231], 0
	v_mfma_f32_16x16x32_bf16 v[48:51], v[178:181], v[232:235], v[48:51]
	v_mfma_f32_16x16x32_bf16 v[44:47], v[182:185], v[228:231], 0
	v_mfma_f32_16x16x32_bf16 v[44:47], v[208:211], v[232:235], v[44:47]
	v_mfma_f32_16x16x32_bf16 v[16:19], v[174:177], v[236:239], 0
	v_mfma_f32_16x16x32_bf16 v[16:19], v[178:181], v[240:243], v[16:19]
	s_setprio 2
	s_barrier
	v_mfma_f32_16x16x32_bf16 v[12:15], v[182:185], v[236:239], 0
	v_mfma_f32_16x16x32_bf16 v[12:15], v[208:211], v[240:243], v[12:15]
	s_setprio 0
	s_add_i32 s25, 0, 0x18000
	v_add_u32_e32 v162, s25, v186
	s_add_i32 s26, 0, 0x1c000
	ds_read_b128 v[136:139], v162
	ds_read_b128 v[140:143], v162 offset:1024
	ds_read_b128 v[144:147], v162 offset:2048
	ds_read_b128 v[170:173], v162 offset:3072
	v_add_u32_e32 v162, s26, v186
	ds_read_b128 v[174:177], v162
	ds_read_b128 v[178:181], v162 offset:1024
	ds_read_b128 v[182:185], v162 offset:2048
	ds_read_b128 v[208:211], v162 offset:3072
	s_add_u32 s10, s64, 0x80000
	s_addc_u32 s11, s65, 0
	s_mov_b32 m0, s75
	v_lshl_add_u64 v[162:163], s[10:11], 0, v[0:1]
	ds_read_b128 v[212:215], v197 offset:32768
	ds_read_b128 v[216:219], v197 offset:33792
	ds_read_b128 v[220:223], v197 offset:34816
	ds_read_b128 v[224:227], v197 offset:35840
	ds_read_b128 v[228:231], v197 offset:36864
	ds_read_b128 v[232:235], v197 offset:37888
	ds_read_b128 v[236:239], v197 offset:38912
	ds_read_b128 v[240:243], v197 offset:39936
	global_load_lds_dwordx4 v[162:163], off
	v_lshl_add_u64 v[162:163], s[10:11], 0, v[148:149]
	s_mov_b32 m0, s76
	s_nop 0
	global_load_lds_dwordx4 v[162:163], off
	s_waitcnt vmcnt(8)
	s_waitcnt lgkmcnt(0)
	s_barrier
	s_setprio 1
	s_waitcnt lgkmcnt(0)
	v_mfma_f32_16x16x32_bf16 v[36:39], v[136:139], v[212:215], v[36:39]
	v_mfma_f32_16x16x32_bf16 v[36:39], v[140:143], v[216:219], v[36:39]
	v_mfma_f32_16x16x32_bf16 v[40:43], v[144:147], v[212:215], v[40:43]
	v_mfma_f32_16x16x32_bf16 v[40:43], v[170:173], v[216:219], v[40:43]
	v_mfma_f32_16x16x32_bf16 v[68:71], v[136:139], v[220:223], v[68:71]
	v_mfma_f32_16x16x32_bf16 v[68:71], v[140:143], v[224:227], v[68:71]
	v_mfma_f32_16x16x32_bf16 v[72:75], v[144:147], v[220:223], v[72:75]
	v_mfma_f32_16x16x32_bf16 v[72:75], v[170:173], v[224:227], v[72:75]
	v_mfma_f32_16x16x32_bf16 v[100:103], v[136:139], v[228:231], v[100:103]
	v_mfma_f32_16x16x32_bf16 v[100:103], v[140:143], v[232:235], v[100:103]
	v_mfma_f32_16x16x32_bf16 v[104:107], v[144:147], v[228:231], v[104:107]
	v_mfma_f32_16x16x32_bf16 v[104:107], v[170:173], v[232:235], v[104:107]
	v_mfma_f32_16x16x32_bf16 v[128:131], v[136:139], v[236:239], v[128:131]
	v_mfma_f32_16x16x32_bf16 v[128:131], v[140:143], v[240:243], v[128:131]
	v_mfma_f32_16x16x32_bf16 v[124:127], v[144:147], v[236:239], v[124:127]
	v_mfma_f32_16x16x32_bf16 v[124:127], v[170:173], v[240:243], v[124:127]
	s_setprio 0
	s_setprio 1
	v_mfma_f32_16x16x32_bf16 v[8:11], v[174:177], v[212:215], v[8:11]
	v_mfma_f32_16x16x32_bf16 v[8:11], v[178:181], v[216:219], v[8:11]
	v_mfma_f32_16x16x32_bf16 v[4:7], v[182:185], v[212:215], v[4:7]
	v_mfma_f32_16x16x32_bf16 v[4:7], v[208:211], v[216:219], v[4:7]
	v_mfma_f32_16x16x32_bf16 v[32:35], v[174:177], v[220:223], v[32:35]
	v_mfma_f32_16x16x32_bf16 v[32:35], v[178:181], v[224:227], v[32:35]
	v_mfma_f32_16x16x32_bf16 v[28:31], v[182:185], v[220:223], v[28:31]
	v_mfma_f32_16x16x32_bf16 v[28:31], v[208:211], v[224:227], v[28:31]
	v_mfma_f32_16x16x32_bf16 v[56:59], v[174:177], v[228:231], v[56:59]
	v_mfma_f32_16x16x32_bf16 v[56:59], v[178:181], v[232:235], v[56:59]
	v_mfma_f32_16x16x32_bf16 v[52:55], v[182:185], v[228:231], v[52:55]
	v_mfma_f32_16x16x32_bf16 v[52:55], v[208:211], v[232:235], v[52:55]
	v_mfma_f32_16x16x32_bf16 v[80:83], v[174:177], v[236:239], v[80:83]
	v_mfma_f32_16x16x32_bf16 v[80:83], v[178:181], v[240:243], v[80:83]
	s_setprio 2
	s_barrier
; #define PG8_STAGE(bufoff, gbase, voff) do { _Pragma("unroll") for (int _i = 0; _i < 2; ++_i) \
;         __builtin_amdgcn_global_load_lds((const unsigned*)((const char*)(gbase) + (voff)[_i]), (LAS unsigned*)(lds + (bufoff) + ldsw + _i * 8192), 16, 0, 0); } while (0)
; #define PG8_LDA(dst, b, h) do { _Pragma("unroll") for (int m = 0; m < 4; ++m) _Pragma("unroll") for (int k = 0; k < 2; ++k) dst[m][k] = *(const LAS bf16x8*)(lds + PG8_SA(b, h) + aoff + m * 2048 + k * 1024); } while (0)
; #define PG8_LDB(dst, b, h) do { _Pragma("unroll") for (int n = 0; n < 2; ++n) _Pragma("unroll") for (int k = 0; k < 2; ++k) dst[n][k] = *(const LAS bf16x8*)(lds + PG8_SB(b, h) + boff + n * 2048 + k * 1024); } while (0)
; #define PG8_WAIT_V(n) asm volatile("s_waitcnt vmcnt(" #n ")" ::: "memory")
; #define PG8_BAR __builtin_amdgcn_s_barrier()
; template <class Epi, class Sched, bool ALIGN_EPI = true>
; __device__ __forceinline__ void gemm_phase(LAS unsigned char* lds, const Gemm g, const Sched& S, const Epi& E) {
;     ...
;         for (int t = 0; t < nt; t += 2) {
;             const bool last = (t == nt - 2);
;             const char* a1 = cA + (size_t)(t + 1) * kstep;
;             const char* a2 = last ? nA : cA + (size_t)(t + 2) * kstep; const char* b2 = last ? nB : cB + (size_t)(t + 2) * kstep;
;             const char* a3 = a2 + kstep; const char* b3 = b2 + kstep;
;             PG8_LDB(B0, 0, 0); PG8_LDB(B1, 0, 1); PG8_SCHED; PG8_LDA(At, 0, 0); PG8_STAGE(PG8_SA(1, 1), a1 + hA, voffA);
;             PG8_WAIT_V(8); PG8_WAIT_L(0); PG8_BAR; PG8_MMA(0, 0, At, B0); PG8_MMA(0, 1, At, B1); PG8_BAR; PG8_SCHED;
;             PG8_LDA(At, 0, 1); PG8_STAGE(PG8_SB(0, 0), b2, voffB); PG8_STAGE(PG8_SB(0, 1), b2 + hB, voffB); PG8_STAGE(PG8_SA(0, 0), a2, voffA);
;             PG8_WAIT_V(8); PG8_WAIT_L(0); PG8_BAR; PG8_MMA(1, 0, At, B0); PG8_MMA(1, 1, At, B1); PG8_BAR; PG8_SCHED;
;             PG8_LDB(B0, 1, 0); PG8_LDB(B1, 1, 1); PG8_SCHED; PG8_LDA(At, 1, 0); PG8_STAGE(PG8_SA(0, 1), a2 + hA, voffA);
;             PG8_WAIT_V(8); PG8_WAIT_L(0); PG8_BAR; PG8_MMA(0, 0, At, B0); PG8_MMA(0, 1, At, B1); PG8_BAR; PG8_SCHED;
;             PG8_LDA(At, 1, 1); PG8_STAGE(PG8_SB(1, 0), b3, voffB); PG8_STAGE(PG8_SB(1, 1), b3 + hB, voffB); PG8_STAGE(PG8_SA(1, 0), a3, voffA);
;             PG8_WAIT_V(8); PG8_WAIT_L(0); PG8_BAR; PG8_MMA(1, 0, At, B0); PG8_MMA(1, 1, At, B1); PG8_BAR; PG8_SCHED;
	v_mfma_f32_16x16x32_bf16 v[76:79], v[182:185], v[236:239], v[76:79]
	v_mfma_f32_16x16x32_bf16 v[76:79], v[208:211], v[240:243], v[76:79]
	s_setprio 0
	s_add_i32 s10, s25, s67
	v_lshl_add_u64 v[162:163], v[244:245], 0, s[86:87]
	s_mov_b32 m0, s10
	ds_read_b128 v[212:215], v197 offset:49152
	ds_read_b128 v[216:219], v197 offset:50176
	ds_read_b128 v[220:223], v197 offset:51200
	ds_read_b128 v[224:227], v197 offset:52224
	ds_read_b128 v[228:231], v197 offset:53248
	ds_read_b128 v[232:235], v197 offset:54272
	ds_read_b128 v[236:239], v197 offset:55296
	ds_read_b128 v[240:243], v197 offset:56320
	global_load_lds_dwordx4 v[162:163], off
	s_add_i32 m0, s10, 0x2000
	s_add_u32 s10, s62, 0x80080
	v_lshl_add_u64 v[162:163], v[246:247], 0, s[86:87]
	s_addc_u32 s11, s63, 0
	s_add_i32 s25, s26, s67
	global_load_lds_dwordx4 v[162:163], off
	v_lshl_add_u64 v[162:163], s[10:11], 0, v[2:3]
	s_mov_b32 m0, s25
	v_lshl_add_u64 v[160:161], v[160:161], 0, s[86:87]
	global_load_lds_dwordx4 v[162:163], off
	v_lshl_add_u64 v[162:163], s[10:11], 0, v[150:151]
	s_add_i32 m0, s25, 0x2000
	s_nop 0
	global_load_lds_dwordx4 v[162:163], off
	v_lshl_add_u64 v[162:163], v[248:249], 0, s[86:87]
	s_mov_b32 m0, s79
	s_nop 0
	global_load_lds_dwordx4 v[162:163], off
	s_mov_b32 m0, s80
	s_nop 0
	global_load_lds_dwordx4 v[160:161], off
	s_waitcnt vmcnt(8)
	s_waitcnt lgkmcnt(0)
	s_barrier
	s_setprio 1
	s_waitcnt lgkmcnt(0)
	v_mfma_f32_16x16x32_bf16 v[120:123], v[136:139], v[212:215], v[120:123]
	v_mfma_f32_16x16x32_bf16 v[120:123], v[140:143], v[216:219], v[120:123]
	v_mfma_f32_16x16x32_bf16 v[116:119], v[144:147], v[212:215], v[116:119]
	v_mfma_f32_16x16x32_bf16 v[116:119], v[170:173], v[216:219], v[116:119]
	v_mfma_f32_16x16x32_bf16 v[96:99], v[136:139], v[220:223], v[96:99]
	v_mfma_f32_16x16x32_bf16 v[96:99], v[140:143], v[224:227], v[96:99]
	v_mfma_f32_16x16x32_bf16 v[92:95], v[144:147], v[220:223], v[92:95]
	v_mfma_f32_16x16x32_bf16 v[92:95], v[170:173], v[224:227], v[92:95]
	v_mfma_f32_16x16x32_bf16 v[64:67], v[136:139], v[228:231], v[64:67]
	v_mfma_f32_16x16x32_bf16 v[64:67], v[140:143], v[232:235], v[64:67]
	v_mfma_f32_16x16x32_bf16 v[60:63], v[144:147], v[228:231], v[60:63]
	v_mfma_f32_16x16x32_bf16 v[60:63], v[170:173], v[232:235], v[60:63]
	v_mfma_f32_16x16x32_bf16 v[24:27], v[136:139], v[236:239], v[24:27]
	v_mfma_f32_16x16x32_bf16 v[24:27], v[140:143], v[240:243], v[24:27]
	v_mfma_f32_16x16x32_bf16 v[20:23], v[144:147], v[236:239], v[20:23]
	v_mfma_f32_16x16x32_bf16 v[20:23], v[170:173], v[240:243], v[20:23]
	s_setprio 0
	s_setprio 1
	v_mfma_f32_16x16x32_bf16 v[112:115], v[174:177], v[212:215], v[112:115]
	v_mfma_f32_16x16x32_bf16 v[112:115], v[178:181], v[216:219], v[112:115]
	v_mfma_f32_16x16x32_bf16 v[108:111], v[182:185], v[212:215], v[108:111]
	v_mfma_f32_16x16x32_bf16 v[108:111], v[208:211], v[216:219], v[108:111]
	v_mfma_f32_16x16x32_bf16 v[88:91], v[174:177], v[220:223], v[88:91]
	v_mfma_f32_16x16x32_bf16 v[88:91], v[178:181], v[224:227], v[88:91]
	v_mfma_f32_16x16x32_bf16 v[84:87], v[182:185], v[220:223], v[84:87]
	v_mfma_f32_16x16x32_bf16 v[84:87], v[208:211], v[224:227], v[84:87]
	v_mfma_f32_16x16x32_bf16 v[48:51], v[174:177], v[228:231], v[48:51]
	v_mfma_f32_16x16x32_bf16 v[48:51], v[178:181], v[232:235], v[48:51]
	v_mfma_f32_16x16x32_bf16 v[44:47], v[182:185], v[228:231], v[44:47]
	v_mfma_f32_16x16x32_bf16 v[44:47], v[208:211], v[232:235], v[44:47]
	v_mfma_f32_16x16x32_bf16 v[16:19], v[174:177], v[236:239], v[16:19]
	v_mfma_f32_16x16x32_bf16 v[16:19], v[178:181], v[240:243], v[16:19]
	s_setprio 2
	s_barrier
	v_mfma_f32_16x16x32_bf16 v[12:15], v[182:185], v[236:239], v[12:15]
	v_mfma_f32_16x16x32_bf16 v[12:15], v[208:211], v[240:243], v[12:15]
	s_setprio 0
	s_add_i32 s24, s24, 2
	s_cmp_gt_u32 s24, 29
	s_mov_b64 s[10:11], vcc
	s_cbranch_scc1 .Lpeel_exit_667
	.p2align	6

;     __device__ bool next(int i, Unit& u) const { if (i >= 2) return false; const int x = c & 7, j = c >> 3; u.pm = 32 * i + 4 * x + (j & 3); u.pn = j >> 2; return true; }
; #define PG8_STAGE(bufoff, gbase, voff) do { _Pragma("unroll") for (int _i = 0; _i < 2; ++_i) \
;         __builtin_amdgcn_global_load_lds((const unsigned*)((const char*)(gbase) + (voff)[_i]), (LAS unsigned*)(lds + (bufoff) + ldsw + _i * 8192), 16, 0, 0); } while (0)
; #define PG8_WAIT_V(n) asm volatile("s_waitcnt vmcnt(" #n ")" ::: "memory")
; #define PG8_WAIT_L(n) asm volatile("s_waitcnt lgkmcnt(" #n ")" ::: "memory")
; #define PG8_BAR __builtin_amdgcn_s_barrier()
;     __device__ __forceinline__ void operator()(f32x4 (&acc)[2][2][4][2], const Unit& u, int wr, int wc, int fr_, int fq_, int wid, int lane_) const {
;     ...
;             const int t = wid * 64 + lane, kind = t >> 6, pr = t & 63, bj = kind >> 2, tap = kind & 3;
;             const float* src = (tap < 3) ? (cw + (size_t)tap * FF2 + bj * FF + u.pn * 128 + 2 * pr) : (cb + bj * FF + u.pn * 128 + 2 * pr);
;             const f32x2 wv = *(const f32x2*)src;
; template <class Epi, class Sched, bool ALIGN_EPI = true>
; __device__ __forceinline__ void gemm_phase(LAS unsigned char* lds, const Gemm g, const Sched& S, const Epi& E) {
;     ...
;         const bool has_next = S.next(ui + 1, nxt);
;         const char* nA = has_next ? (const char*)g.A + ((size_t)nxt.pm * BM * g.lda + (size_t)nxt.pn * g.a_pn_off) * 2 : cA; const char* nB = has_next ? (const char*)g.Bt + (size_t)nxt.pn * BM * g.ldb * 2 : cB;
;         for (int t = 0; t < nt; t += 2) {
;             const bool last = (t == nt - 2);
;             const char* a1 = cA + (size_t)(t + 1) * kstep;
;             const char* a2 = last ? nA : cA + (size_t)(t + 2) * kstep; const char* b2 = last ? nB : cB + (size_t)(t + 2) * kstep;
;             const char* a3 = a2 + kstep; const char* b3 = b2 + kstep;
;             PG8_LDB(B0, 0, 0); PG8_LDB(B1, 0, 1); PG8_SCHED; PG8_LDA(At, 0, 0); PG8_STAGE(PG8_SA(1, 1), a1 + hA, voffA);
;             PG8_WAIT_V(8); PG8_WAIT_L(0); PG8_BAR; PG8_MMA(0, 0, At, B0); PG8_MMA(0, 1, At, B1); PG8_BAR; PG8_SCHED;
;             PG8_LDA(At, 0, 1); PG8_STAGE(PG8_SB(0, 0), b2, voffB); PG8_STAGE(PG8_SB(0, 1), b2 + hB, voffB); PG8_STAGE(PG8_SA(0, 0), a2, voffA);
;             PG8_WAIT_V(8); PG8_WAIT_L(0); PG8_BAR; PG8_MMA(1, 0, At, B0); PG8_MMA(1, 1, At, B1); PG8_BAR; PG8_SCHED;
.LBB0_827:
	s_ashr_i32 s39, s38, 31
	s_lshl_b64 s[16:17], s[38:39], 20
	s_add_u32 s40, s46, s16
	s_addc_u32 s41, s47, s17
	s_and_b64 s[16:17], s[4:5], exec
	s_cselect_b32 s16, s41, s7
	s_cselect_b32 s17, s40, s6
	s_ashr_i32 s15, s14, 31
	s_lshl_b64 s[18:19], s[14:15], 20
	s_add_u32 s42, s53, s18
	s_addc_u32 s43, s60, s19
	s_and_b64 s[18:19], s[4:5], exec
	s_cselect_b32 s15, s43, s45
	s_cselect_b32 s18, s42, s44
	s_add_u32 s6, s6, 0x80080
	s_addc_u32 s7, s7, 0
	s_add_u32 s19, s44, 0x100
	s_addc_u32 s24, s45, 0
	s_mov_b32 s25, -2
	v_add_u32_e32 v228, s77, v158
	v_ashrrev_i32_e32 v229, 6, v228
	v_and_b32_e32 v230, 3, v229
	v_lshrrev_b32_e32 v231, 8, v228
	v_mul_u32_u24_e32 v228, 0x2c00, v230
	v_lshlrev_b32_e32 v228, 2, v228
	v_mov_b32_e32 v229, 0
	v_lshl_add_u64 v[232:233], s[2:3], 0, v[228:229]
	v_mov_b32_e32 v228, s9
	v_cmp_eq_u32_e32 vcc, 3, v230
	v_mul_i32_i24_e32 v234, 0x1600, v231
	v_ashrrev_i32_e32 v235, 31, v234
	v_cndmask_b32_e32 v233, v233, v228, vcc
	v_mov_b32_e32 v228, s8
	v_cndmask_b32_e32 v232, v232, v228, vcc
	v_lshl_add_u64 v[232:233], v[234:235], 2, v[232:233]
	s_lshl_b32 s26, s82, 7
	s_ashr_i32 s27, s26, 31
	v_lshl_add_u64 v[232:233], s[26:27], 2, v[232:233]
	v_and_b32_e32 v228, 63, v158
	v_lshlrev_b32_e32 v228, 3, v228
	v_mov_b32_e32 v229, 0
	v_lshl_add_u64 v[232:233], v[232:233], 0, v[228:229]
	global_load_dwordx2 v[226:227], v[232:233], off
	s_add_u32 s26, s6, 0xfff80080
	s_addc_u32 s27, s7, -1
	s_add_i32 s30, 0, 0x10000
	s_cmp_eq_u32 s25, 28
	s_cselect_b32 s59, s16, s27
	s_cselect_b32 s58, s17, s26
	v_add_u32_e32 v2, s30, v204
	s_cselect_b32 s45, s15, s24
	s_cselect_b32 s44, s18, s19
	s_add_i32 s31, 0, 0x14000
	ds_read_b128 v[132:135], v2
	ds_read_b128 v[136:139], v2 offset:1024
	ds_read_b128 v[140:143], v2 offset:2048
	ds_read_b128 v[144:147], v2 offset:3072
	v_add_u32_e32 v2, s31, v204
	ds_read_b128 v[148:151], v2
	ds_read_b128 v[152:155], v2 offset:1024
	ds_read_b128 v[174:177], v2 offset:2048
	ds_read_b128 v[178:181], v2 offset:3072
	v_lshl_add_u64 v[156:157], s[6:7], 0, v[170:171]
	s_add_i32 m0, s62, 0xc000
	ds_read_b128 v[182:185], v205
	ds_read_b128 v[186:189], v205 offset:1024
	ds_read_b128 v[190:193], v205 offset:2048
	ds_read_b128 v[194:197], v205 offset:3072
	ds_read_b128 v[206:209], v205 offset:4096
	ds_read_b128 v[210:213], v205 offset:5120
	ds_read_b128 v[214:217], v205 offset:6144
	ds_read_b128 v[218:221], v205 offset:7168
	global_load_lds_dwordx4 v[156:157], off
	v_lshl_add_u64 v[156:157], s[6:7], 0, v[172:173]
	s_add_i32 m0, s62, 0xe000
	s_nop 0
	global_load_lds_dwordx4 v[156:157], off
	s_waitcnt vmcnt(8)
	s_waitcnt lgkmcnt(0)
	s_barrier
	s_setprio 1
	s_waitcnt lgkmcnt(0)
	v_mfma_f32_16x16x32_bf16 v[116:119], v[132:135], v[182:185], 0
	v_mfma_f32_16x16x32_bf16 v[116:119], v[136:139], v[186:189], v[116:119]
	v_mfma_f32_16x16x32_bf16 v[100:103], v[140:143], v[182:185], 0
	v_mfma_f32_16x16x32_bf16 v[100:103], v[144:147], v[186:189], v[100:103]
	v_mfma_f32_16x16x32_bf16 v[108:111], v[132:135], v[190:193], 0
	v_mfma_f32_16x16x32_bf16 v[108:111], v[136:139], v[194:197], v[108:111]
	v_mfma_f32_16x16x32_bf16 v[96:99], v[140:143], v[190:193], 0
	v_mfma_f32_16x16x32_bf16 v[96:99], v[144:147], v[194:197], v[96:99]
	v_mfma_f32_16x16x32_bf16 v[88:91], v[132:135], v[206:209], 0
	v_mfma_f32_16x16x32_bf16 v[88:91], v[136:139], v[210:213], v[88:91]
	v_mfma_f32_16x16x32_bf16 v[84:87], v[140:143], v[206:209], 0
	v_mfma_f32_16x16x32_bf16 v[84:87], v[144:147], v[210:213], v[84:87]
	v_mfma_f32_16x16x32_bf16 v[72:75], v[132:135], v[214:217], 0
	v_mfma_f32_16x16x32_bf16 v[72:75], v[136:139], v[218:221], v[72:75]
	v_mfma_f32_16x16x32_bf16 v[80:83], v[140:143], v[214:217], 0
	v_mfma_f32_16x16x32_bf16 v[80:83], v[144:147], v[218:221], v[80:83]
	s_setprio 0
	s_setprio 1
	v_mfma_f32_16x16x32_bf16 v[128:131], v[148:151], v[182:185], 0
	v_mfma_f32_16x16x32_bf16 v[128:131], v[152:155], v[186:189], v[128:131]
	v_mfma_f32_16x16x32_bf16 v[44:47], v[174:177], v[182:185], 0
	v_mfma_f32_16x16x32_bf16 v[44:47], v[178:181], v[186:189], v[44:47]
	v_mfma_f32_16x16x32_bf16 v[124:127], v[148:151], v[190:193], 0
	v_mfma_f32_16x16x32_bf16 v[124:127], v[152:155], v[194:197], v[124:127]
	v_mfma_f32_16x16x32_bf16 v[36:39], v[174:177], v[190:193], 0
	v_mfma_f32_16x16x32_bf16 v[36:39], v[178:181], v[194:197], v[36:39]
	v_mfma_f32_16x16x32_bf16 v[120:123], v[148:151], v[206:209], 0
	v_mfma_f32_16x16x32_bf16 v[120:123], v[152:155], v[210:213], v[120:123]
	v_mfma_f32_16x16x32_bf16 v[32:35], v[174:177], v[206:209], 0
	v_mfma_f32_16x16x32_bf16 v[32:35], v[178:181], v[210:213], v[32:35]
	v_mfma_f32_16x16x32_bf16 v[112:115], v[148:151], v[214:217], 0
	v_mfma_f32_16x16x32_bf16 v[112:115], v[152:155], v[218:221], v[112:115]
	s_setprio 2
	s_barrier
	v_mfma_f32_16x16x32_bf16 v[28:31], v[174:177], v[214:217], 0
	v_mfma_f32_16x16x32_bf16 v[28:31], v[178:181], v[218:221], v[28:31]
	s_setprio 0
	s_add_i32 s26, s30, s61
	v_lshl_add_u64 v[156:157], s[44:45], 0, v[166:167]
	s_mov_b32 m0, s26
	ds_read_b128 v[182:185], v205 offset:16384
	ds_read_b128 v[186:189], v205 offset:17408
	ds_read_b128 v[190:193], v205 offset:18432
	ds_read_b128 v[194:197], v205 offset:19456
	ds_read_b128 v[206:209], v205 offset:20480
	ds_read_b128 v[210:213], v205 offset:21504
	ds_read_b128 v[214:217], v205 offset:22528
	ds_read_b128 v[218:221], v205 offset:23552
	global_load_lds_dwordx4 v[156:157], off
	s_add_i32 m0, s26, 0x2000
	s_add_u32 s26, s44, 0x80000
	v_lshl_add_u64 v[160:161], s[44:45], 0, v[0:1]
	s_addc_u32 s27, s45, 0
	s_add_i32 s30, s31, s61
	global_load_lds_dwordx4 v[160:161], off
	v_lshl_add_u64 v[162:163], s[26:27], 0, v[166:167]
	s_mov_b32 m0, s30
	v_lshl_add_u64 v[222:223], s[58:59], 0, v[164:165]
	global_load_lds_dwordx4 v[162:163], off
	v_lshl_add_u64 v[162:163], s[26:27], 0, v[0:1]
	s_add_i32 m0, s30, 0x2000
	s_nop 0
	global_load_lds_dwordx4 v[162:163], off
	v_lshl_add_u64 v[162:163], s[58:59], 0, v[168:169]
	s_mov_b32 m0, s62
	s_nop 0
	global_load_lds_dwordx4 v[162:163], off
	s_mov_b32 m0, s63
	s_nop 0
	global_load_lds_dwordx4 v[222:223], off
	s_waitcnt vmcnt(8)
	s_waitcnt lgkmcnt(0)
	s_barrier
; #define PG8_STAGE(bufoff, gbase, voff) do { _Pragma("unroll") for (int _i = 0; _i < 2; ++_i) \
;         __builtin_amdgcn_global_load_lds((const unsigned*)((const char*)(gbase) + (voff)[_i]), (LAS unsigned*)(lds + (bufoff) + ldsw + _i * 8192), 16, 0, 0); } while (0)
; #define PG8_LDA(dst, b, h) do { _Pragma("unroll") for (int m = 0; m < 4; ++m) _Pragma("unroll") for (int k = 0; k < 2; ++k) dst[m][k] = *(const LAS bf16x8*)(lds + PG8_SA(b, h) + aoff + m * 2048 + k * 1024); } while (0)
; #define PG8_LDB(dst, b, h) do { _Pragma("unroll") for (int n = 0; n < 2; ++n) _Pragma("unroll") for (int k = 0; k < 2; ++k) dst[n][k] = *(const LAS bf16x8*)(lds + PG8_SB(b, h) + boff + n * 2048 + k * 1024); } while (0)
; #define PG8_MMA(ai, bj, At, Bt) do { __builtin_amdgcn_s_setprio(1); _Pragma("unroll") for (int m = 0; m < 4; ++m) _Pragma("unroll") for (int n = 0; n < 2; ++n) _Pragma("unroll") for (int k = 0; k < 2; ++k) \
;         acc[ai][bj][m][n] = __builtin_amdgcn_mfma_f32_16x16x32_bf16(Bt[n][k], At[m][k], acc[ai][bj][m][n], 0, 0, 0); __builtin_amdgcn_s_setprio(0); } while (0)
; #define PG8_WAIT_V(n) asm volatile("s_waitcnt vmcnt(" #n ")" ::: "memory")
; #define PG8_WAIT_L(n) asm volatile("s_waitcnt lgkmcnt(" #n ")" ::: "memory")
; #define PG8_BAR __builtin_amdgcn_s_barrier()
; #define PG8_SCHED __builtin_amdgcn_sched_barrier(0)
; template <class Epi, class Sched, bool ALIGN_EPI = true>
; __device__ __forceinline__ void gemm_phase(LAS unsigned char* lds, const Gemm g, const Sched& S, const Epi& E) {
;     ...
;             PG8_WAIT_V(8); PG8_WAIT_L(0); PG8_BAR; PG8_MMA(1, 0, At, B0); PG8_MMA(1, 1, At, B1); PG8_BAR; PG8_SCHED;
;             PG8_LDB(B0, 1, 0); PG8_LDB(B1, 1, 1); PG8_SCHED; PG8_LDA(At, 1, 0); PG8_STAGE(PG8_SA(0, 1), a2 + hA, voffA);
;             PG8_WAIT_V(8); PG8_WAIT_L(0); PG8_BAR; PG8_MMA(0, 0, At, B0); PG8_MMA(0, 1, At, B1); PG8_BAR; PG8_SCHED;
;             PG8_LDA(At, 1, 1); PG8_STAGE(PG8_SB(1, 0), b3, voffB); PG8_STAGE(PG8_SB(1, 1), b3 + hB, voffB); PG8_STAGE(PG8_SA(1, 0), a3, voffA);
;             PG8_WAIT_V(8); PG8_WAIT_L(0); PG8_BAR; PG8_MMA(1, 0, At, B0); PG8_MMA(1, 1, At, B1); PG8_BAR; PG8_SCHED;
	s_setprio 1
	s_waitcnt lgkmcnt(0)
	v_mfma_f32_16x16x32_bf16 v[60:63], v[132:135], v[182:185], 0
	v_mfma_f32_16x16x32_bf16 v[60:63], v[136:139], v[186:189], v[60:63]
	v_mfma_f32_16x16x32_bf16 v[68:71], v[140:143], v[182:185], 0
	v_mfma_f32_16x16x32_bf16 v[68:71], v[144:147], v[186:189], v[68:71]
	v_mfma_f32_16x16x32_bf16 v[40:43], v[132:135], v[190:193], 0
	v_mfma_f32_16x16x32_bf16 v[40:43], v[136:139], v[194:197], v[40:43]
	v_mfma_f32_16x16x32_bf16 v[64:67], v[140:143], v[190:193], 0
	v_mfma_f32_16x16x32_bf16 v[64:67], v[144:147], v[194:197], v[64:67]
	v_mfma_f32_16x16x32_bf16 v[24:27], v[132:135], v[206:209], 0
	v_mfma_f32_16x16x32_bf16 v[24:27], v[136:139], v[210:213], v[24:27]
	v_mfma_f32_16x16x32_bf16 v[56:59], v[140:143], v[206:209], 0
	v_mfma_f32_16x16x32_bf16 v[56:59], v[144:147], v[210:213], v[56:59]
	v_mfma_f32_16x16x32_bf16 v[12:15], v[132:135], v[214:217], 0
	v_mfma_f32_16x16x32_bf16 v[12:15], v[136:139], v[218:221], v[12:15]
	v_mfma_f32_16x16x32_bf16 v[48:51], v[140:143], v[214:217], 0
	v_mfma_f32_16x16x32_bf16 v[48:51], v[144:147], v[218:221], v[48:51]
	s_setprio 0
	s_setprio 1
	v_mfma_f32_16x16x32_bf16 v[104:107], v[148:151], v[182:185], 0
	v_mfma_f32_16x16x32_bf16 v[104:107], v[152:155], v[186:189], v[104:107]
	v_mfma_f32_16x16x32_bf16 v[20:23], v[174:177], v[182:185], 0
	v_mfma_f32_16x16x32_bf16 v[20:23], v[178:181], v[186:189], v[20:23]
	v_mfma_f32_16x16x32_bf16 v[92:95], v[148:151], v[190:193], 0
	v_mfma_f32_16x16x32_bf16 v[92:95], v[152:155], v[194:197], v[92:95]
	v_mfma_f32_16x16x32_bf16 v[16:19], v[174:177], v[190:193], 0
	v_mfma_f32_16x16x32_bf16 v[16:19], v[178:181], v[194:197], v[16:19]
	v_mfma_f32_16x16x32_bf16 v[76:79], v[148:151], v[206:209], 0
	v_mfma_f32_16x16x32_bf16 v[76:79], v[152:155], v[210:213], v[76:79]
	v_mfma_f32_16x16x32_bf16 v[8:11], v[174:177], v[206:209], 0
	v_mfma_f32_16x16x32_bf16 v[8:11], v[178:181], v[210:213], v[8:11]
	v_mfma_f32_16x16x32_bf16 v[52:55], v[148:151], v[214:217], 0
	v_mfma_f32_16x16x32_bf16 v[52:55], v[152:155], v[218:221], v[52:55]
	s_setprio 2
	s_barrier
	v_mfma_f32_16x16x32_bf16 v[4:7], v[174:177], v[214:217], 0
	v_mfma_f32_16x16x32_bf16 v[4:7], v[178:181], v[218:221], v[4:7]
	s_setprio 0
	s_add_i32 s30, 0, 0x18000
	v_add_u32_e32 v2, s30, v204
	s_add_i32 s31, 0, 0x1c000
	ds_read_b128 v[132:135], v2
	ds_read_b128 v[136:139], v2 offset:1024
	ds_read_b128 v[140:143], v2 offset:2048
	ds_read_b128 v[144:147], v2 offset:3072
	v_add_u32_e32 v2, s31, v204
	ds_read_b128 v[148:151], v2
	ds_read_b128 v[152:155], v2 offset:1024
	ds_read_b128 v[174:177], v2 offset:2048
	ds_read_b128 v[178:181], v2 offset:3072
	s_add_u32 s26, s58, 0x80000
	s_addc_u32 s27, s59, 0
	s_mov_b32 m0, s64
	v_lshl_add_u64 v[224:225], s[26:27], 0, v[168:169]
	ds_read_b128 v[182:185], v205 offset:32768
	ds_read_b128 v[186:189], v205 offset:33792
	ds_read_b128 v[190:193], v205 offset:34816
	ds_read_b128 v[194:197], v205 offset:35840
	ds_read_b128 v[206:209], v205 offset:36864
	ds_read_b128 v[210:213], v205 offset:37888
	ds_read_b128 v[214:217], v205 offset:38912
	ds_read_b128 v[218:221], v205 offset:39936
	global_load_lds_dwordx4 v[224:225], off
	v_lshl_add_u64 v[224:225], s[26:27], 0, v[164:165]
	s_mov_b32 m0, s65
	s_nop 0
	global_load_lds_dwordx4 v[224:225], off
	s_waitcnt vmcnt(8)
	s_waitcnt lgkmcnt(0)
	s_barrier
	s_setprio 1
	s_waitcnt lgkmcnt(0)
	v_mfma_f32_16x16x32_bf16 v[116:119], v[132:135], v[182:185], v[116:119]
	v_mfma_f32_16x16x32_bf16 v[116:119], v[136:139], v[186:189], v[116:119]
	v_mfma_f32_16x16x32_bf16 v[100:103], v[140:143], v[182:185], v[100:103]
	v_mfma_f32_16x16x32_bf16 v[100:103], v[144:147], v[186:189], v[100:103]
	v_mfma_f32_16x16x32_bf16 v[108:111], v[132:135], v[190:193], v[108:111]
	v_mfma_f32_16x16x32_bf16 v[108:111], v[136:139], v[194:197], v[108:111]
	v_mfma_f32_16x16x32_bf16 v[96:99], v[140:143], v[190:193], v[96:99]
	v_mfma_f32_16x16x32_bf16 v[96:99], v[144:147], v[194:197], v[96:99]
	v_mfma_f32_16x16x32_bf16 v[88:91], v[132:135], v[206:209], v[88:91]
	v_mfma_f32_16x16x32_bf16 v[88:91], v[136:139], v[210:213], v[88:91]
	v_mfma_f32_16x16x32_bf16 v[84:87], v[140:143], v[206:209], v[84:87]
	v_mfma_f32_16x16x32_bf16 v[84:87], v[144:147], v[210:213], v[84:87]
	v_mfma_f32_16x16x32_bf16 v[72:75], v[132:135], v[214:217], v[72:75]
	v_mfma_f32_16x16x32_bf16 v[72:75], v[136:139], v[218:221], v[72:75]
	v_mfma_f32_16x16x32_bf16 v[80:83], v[140:143], v[214:217], v[80:83]
	v_mfma_f32_16x16x32_bf16 v[80:83], v[144:147], v[218:221], v[80:83]
	s_setprio 0
	s_setprio 1
	v_mfma_f32_16x16x32_bf16 v[128:131], v[148:151], v[182:185], v[128:131]
	v_mfma_f32_16x16x32_bf16 v[128:131], v[152:155], v[186:189], v[128:131]
	v_mfma_f32_16x16x32_bf16 v[44:47], v[174:177], v[182:185], v[44:47]
	v_mfma_f32_16x16x32_bf16 v[44:47], v[178:181], v[186:189], v[44:47]
	v_mfma_f32_16x16x32_bf16 v[124:127], v[148:151], v[190:193], v[124:127]
	v_mfma_f32_16x16x32_bf16 v[124:127], v[152:155], v[194:197], v[124:127]
	v_mfma_f32_16x16x32_bf16 v[36:39], v[174:177], v[190:193], v[36:39]
	v_mfma_f32_16x16x32_bf16 v[36:39], v[178:181], v[194:197], v[36:39]
	v_mfma_f32_16x16x32_bf16 v[120:123], v[148:151], v[206:209], v[120:123]
	v_mfma_f32_16x16x32_bf16 v[120:123], v[152:155], v[210:213], v[120:123]
	v_mfma_f32_16x16x32_bf16 v[32:35], v[174:177], v[206:209], v[32:35]
	v_mfma_f32_16x16x32_bf16 v[32:35], v[178:181], v[210:213], v[32:35]
	v_mfma_f32_16x16x32_bf16 v[112:115], v[148:151], v[214:217], v[112:115]
	v_mfma_f32_16x16x32_bf16 v[112:115], v[152:155], v[218:221], v[112:115]
	s_setprio 2
	s_barrier
; #define PG8_STAGE(bufoff, gbase, voff) do { _Pragma("unroll") for (int _i = 0; _i < 2; ++_i) \
;         __builtin_amdgcn_global_load_lds((const unsigned*)((const char*)(gbase) + (voff)[_i]), (LAS unsigned*)(lds + (bufoff) + ldsw + _i * 8192), 16, 0, 0); } while (0)
; #define PG8_LDA(dst, b, h) do { _Pragma("unroll") for (int m = 0; m < 4; ++m) _Pragma("unroll") for (int k = 0; k < 2; ++k) dst[m][k] = *(const LAS bf16x8*)(lds + PG8_SA(b, h) + aoff + m * 2048 + k * 1024); } while (0)
; #define PG8_LDB(dst, b, h) do { _Pragma("unroll") for (int n = 0; n < 2; ++n) _Pragma("unroll") for (int k = 0; k < 2; ++k) dst[n][k] = *(const LAS bf16x8*)(lds + PG8_SB(b, h) + boff + n * 2048 + k * 1024); } while (0)
; #define PG8_WAIT_V(n) asm volatile("s_waitcnt vmcnt(" #n ")" ::: "memory")
; #define PG8_WAIT_L(n) asm volatile("s_waitcnt lgkmcnt(" #n ")" ::: "memory")
; #define PG8_BAR __builtin_amdgcn_s_barrier()
; #define PG8_SCHED __builtin_amdgcn_sched_barrier(0)
; template <class Epi, class Sched, bool ALIGN_EPI = true>
; __device__ __forceinline__ void gemm_phase(LAS unsigned char* lds, const Gemm g, const Sched& S, const Epi& E) {
;     ...
;             const char* a2 = last ? nA : cA + (size_t)(t + 2) * kstep; const char* b2 = last ? nB : cB + (size_t)(t + 2) * kstep;
;             const char* a3 = a2 + kstep; const char* b3 = b2 + kstep;
;             PG8_LDB(B0, 0, 0); PG8_LDB(B1, 0, 1); PG8_SCHED; PG8_LDA(At, 0, 0); PG8_STAGE(PG8_SA(1, 1), a1 + hA, voffA);
;             PG8_WAIT_V(8); PG8_WAIT_L(0); PG8_BAR; PG8_MMA(0, 0, At, B0); PG8_MMA(0, 1, At, B1); PG8_BAR; PG8_SCHED;
;             PG8_LDA(At, 0, 1); PG8_STAGE(PG8_SB(0, 0), b2, voffB); PG8_STAGE(PG8_SB(0, 1), b2 + hB, voffB); PG8_STAGE(PG8_SA(0, 0), a2, voffA);
;             PG8_WAIT_V(8); PG8_WAIT_L(0); PG8_BAR; PG8_MMA(1, 0, At, B0); PG8_MMA(1, 1, At, B1); PG8_BAR; PG8_SCHED;
;             PG8_LDB(B0, 1, 0); PG8_LDB(B1, 1, 1); PG8_SCHED; PG8_LDA(At, 1, 0); PG8_STAGE(PG8_SA(0, 1), a2 + hA, voffA);
;             PG8_WAIT_V(8); PG8_WAIT_L(0); PG8_BAR; PG8_MMA(0, 0, At, B0); PG8_MMA(0, 1, At, B1); PG8_BAR; PG8_SCHED;
;             PG8_LDA(At, 1, 1); PG8_STAGE(PG8_SB(1, 0), b3, voffB); PG8_STAGE(PG8_SB(1, 1), b3 + hB, voffB); PG8_STAGE(PG8_SA(1, 0), a3, voffA);
;             PG8_WAIT_V(8); PG8_WAIT_L(0); PG8_BAR; PG8_MMA(1, 0, At, B0); PG8_MMA(1, 1, At, B1); PG8_BAR; PG8_SCHED;
	v_mfma_f32_16x16x32_bf16 v[28:31], v[174:177], v[214:217], v[28:31]
	v_mfma_f32_16x16x32_bf16 v[28:31], v[178:181], v[218:221], v[28:31]
	s_setprio 0
	s_add_i32 s26, s30, s61
	v_lshl_add_u64 v[156:157], v[156:157], 0, s[86:87]
	s_mov_b32 m0, s26
	ds_read_b128 v[182:185], v205 offset:49152
	ds_read_b128 v[186:189], v205 offset:50176
	ds_read_b128 v[190:193], v205 offset:51200
	ds_read_b128 v[194:197], v205 offset:52224
	ds_read_b128 v[206:209], v205 offset:53248
	ds_read_b128 v[210:213], v205 offset:54272
	ds_read_b128 v[214:217], v205 offset:55296
	ds_read_b128 v[218:221], v205 offset:56320
	global_load_lds_dwordx4 v[156:157], off
	s_add_i32 m0, s26, 0x2000
	s_add_u32 s26, s44, 0x80080
	v_lshl_add_u64 v[156:157], v[160:161], 0, s[86:87]
	s_addc_u32 s27, s45, 0
	s_add_i32 s30, s31, s61
	global_load_lds_dwordx4 v[156:157], off
	v_lshl_add_u64 v[156:157], s[26:27], 0, v[166:167]
	s_mov_b32 m0, s30
	s_nop 0
	global_load_lds_dwordx4 v[156:157], off
	v_lshl_add_u64 v[156:157], s[26:27], 0, v[0:1]
	s_add_i32 m0, s30, 0x2000
	s_nop 0
	global_load_lds_dwordx4 v[156:157], off
	v_lshl_add_u64 v[156:157], v[162:163], 0, s[86:87]
	s_mov_b32 m0, s75
	s_nop 0
	global_load_lds_dwordx4 v[156:157], off
	v_lshl_add_u64 v[156:157], v[222:223], 0, s[86:87]
	s_mov_b32 m0, s76
	s_nop 0
	global_load_lds_dwordx4 v[156:157], off
	s_waitcnt vmcnt(8)
	s_waitcnt lgkmcnt(0)
	s_barrier
	s_setprio 1
	s_waitcnt lgkmcnt(0)
	v_mfma_f32_16x16x32_bf16 v[60:63], v[132:135], v[182:185], v[60:63]
	v_mfma_f32_16x16x32_bf16 v[60:63], v[136:139], v[186:189], v[60:63]
	s_add_i32 s25, s25, 2
	s_add_u32 s6, s6, 0x100
	v_mfma_f32_16x16x32_bf16 v[68:71], v[140:143], v[182:185], v[68:71]
	v_mfma_f32_16x16x32_bf16 v[68:71], v[144:147], v[186:189], v[68:71]
	s_addc_u32 s7, s7, 0
	s_add_u32 s19, s19, 0x100
	v_mfma_f32_16x16x32_bf16 v[40:43], v[132:135], v[190:193], v[40:43]
	v_mfma_f32_16x16x32_bf16 v[40:43], v[136:139], v[194:197], v[40:43]
	s_addc_u32 s24, s24, 0
	s_add_u32 s26, s6, 0xfff80080
	v_mfma_f32_16x16x32_bf16 v[64:67], v[140:143], v[190:193], v[64:67]
	v_mfma_f32_16x16x32_bf16 v[64:67], v[144:147], v[194:197], v[64:67]
	s_addc_u32 s27, s7, -1
	s_add_i32 s30, 0, 0x10000
	v_mfma_f32_16x16x32_bf16 v[24:27], v[132:135], v[206:209], v[24:27]
	v_mfma_f32_16x16x32_bf16 v[24:27], v[136:139], v[210:213], v[24:27]
	s_cmp_eq_u32 s25, 28
	s_cselect_b32 s59, s16, s27
	v_mfma_f32_16x16x32_bf16 v[56:59], v[140:143], v[206:209], v[56:59]
	v_mfma_f32_16x16x32_bf16 v[56:59], v[144:147], v[210:213], v[56:59]
	s_cselect_b32 s58, s17, s26
	s_cselect_b32 s45, s15, s24
	v_mfma_f32_16x16x32_bf16 v[12:15], v[132:135], v[214:217], v[12:15]
	v_mfma_f32_16x16x32_bf16 v[12:15], v[136:139], v[218:221], v[12:15]
	s_cselect_b32 s44, s18, s19
	s_add_i32 s31, 0, 0x14000
	v_mfma_f32_16x16x32_bf16 v[48:51], v[140:143], v[214:217], v[48:51]
	v_mfma_f32_16x16x32_bf16 v[48:51], v[144:147], v[218:221], v[48:51]
	s_setprio 0
	s_setprio 1
	v_mfma_f32_16x16x32_bf16 v[104:107], v[148:151], v[182:185], v[104:107]
	v_mfma_f32_16x16x32_bf16 v[104:107], v[152:155], v[186:189], v[104:107]
	v_mfma_f32_16x16x32_bf16 v[20:23], v[174:177], v[182:185], v[20:23]
	v_mfma_f32_16x16x32_bf16 v[20:23], v[178:181], v[186:189], v[20:23]
	v_mfma_f32_16x16x32_bf16 v[92:95], v[148:151], v[190:193], v[92:95]
	v_mfma_f32_16x16x32_bf16 v[92:95], v[152:155], v[194:197], v[92:95]
	v_mfma_f32_16x16x32_bf16 v[16:19], v[174:177], v[190:193], v[16:19]
	v_mfma_f32_16x16x32_bf16 v[16:19], v[178:181], v[194:197], v[16:19]
	v_mfma_f32_16x16x32_bf16 v[76:79], v[148:151], v[206:209], v[76:79]
	v_mfma_f32_16x16x32_bf16 v[76:79], v[152:155], v[210:213], v[76:79]
	v_mfma_f32_16x16x32_bf16 v[8:11], v[174:177], v[206:209], v[8:11]
	v_mfma_f32_16x16x32_bf16 v[8:11], v[178:181], v[210:213], v[8:11]
	v_mfma_f32_16x16x32_bf16 v[52:55], v[148:151], v[214:217], v[52:55]
	v_mfma_f32_16x16x32_bf16 v[52:55], v[152:155], v[218:221], v[52:55]
	s_setprio 2
	s_barrier
	v_mfma_f32_16x16x32_bf16 v[4:7], v[174:177], v[214:217], v[4:7]
	v_mfma_f32_16x16x32_bf16 v[4:7], v[178:181], v[218:221], v[4:7]
	s_setprio 0
	s_cmp_gt_u32 s25, 29
	s_cbranch_scc1 .Lpeel_exit_828
	.p2align	6

;     __device__ bool next(int i, Unit& u) const { if (i >= 2) return false; const int x = c & 7, j = c >> 3; u.pm = 32 * i + 4 * x + (j & 3); u.pn = j >> 2; return true; }
; #define PG8_STAGE(bufoff, gbase, voff) do { _Pragma("unroll") for (int _i = 0; _i < 2; ++_i) \
;         __builtin_amdgcn_global_load_lds((const unsigned*)((const char*)(gbase) + (voff)[_i]), (LAS unsigned*)(lds + (bufoff) + ldsw + _i * 8192), 16, 0, 0); } while (0)
; #define PG8_LDA(dst, b, h) do { _Pragma("unroll") for (int m = 0; m < 4; ++m) _Pragma("unroll") for (int k = 0; k < 2; ++k) dst[m][k] = *(const LAS bf16x8*)(lds + PG8_SA(b, h) + aoff + m * 2048 + k * 1024); } while (0)
; #define PG8_LDB(dst, b, h) do { _Pragma("unroll") for (int n = 0; n < 2; ++n) _Pragma("unroll") for (int k = 0; k < 2; ++k) dst[n][k] = *(const LAS bf16x8*)(lds + PG8_SB(b, h) + boff + n * 2048 + k * 1024); } while (0)
; #define PG8_WAIT_V(n) asm volatile("s_waitcnt vmcnt(" #n ")" ::: "memory")
; #define PG8_WAIT_L(n) asm volatile("s_waitcnt lgkmcnt(" #n ")" ::: "memory")
; #define PG8_BAR __builtin_amdgcn_s_barrier()
; template <class Epi, class Sched, bool ALIGN_EPI = true>
; __device__ __forceinline__ void gemm_phase(LAS unsigned char* lds, const Gemm g, const Sched& S, const Epi& E) {
;     ...
;         const bool has_next = S.next(ui + 1, nxt);
;         const char* nA = has_next ? (const char*)g.A + ((size_t)nxt.pm * BM * g.lda + (size_t)nxt.pn * g.a_pn_off) * 2 : cA; const char* nB = has_next ? (const char*)g.Bt + (size_t)nxt.pn * BM * g.ldb * 2 : cB;
;         for (int t = 0; t < nt; t += 2) {
;             const bool last = (t == nt - 2);
;             const char* a1 = cA + (size_t)(t + 1) * kstep;
;             const char* a2 = last ? nA : cA + (size_t)(t + 2) * kstep; const char* b2 = last ? nB : cB + (size_t)(t + 2) * kstep;
;             const char* a3 = a2 + kstep; const char* b3 = b2 + kstep;
;             PG8_LDB(B0, 0, 0); PG8_LDB(B1, 0, 1); PG8_SCHED; PG8_LDA(At, 0, 0); PG8_STAGE(PG8_SA(1, 1), a1 + hA, voffA);
;             PG8_WAIT_V(8); PG8_WAIT_L(0); PG8_BAR; PG8_MMA(0, 0, At, B0); PG8_MMA(0, 1, At, B1); PG8_BAR; PG8_SCHED;
;             PG8_LDA(At, 0, 1); PG8_STAGE(PG8_SB(0, 0), b2, voffB); PG8_STAGE(PG8_SB(0, 1), b2 + hB, voffB); PG8_STAGE(PG8_SA(0, 0), a2, voffA);
;             PG8_WAIT_V(8); PG8_WAIT_L(0); PG8_BAR; PG8_MMA(1, 0, At, B0); PG8_MMA(1, 1, At, B1); PG8_BAR; PG8_SCHED;
.LBB0_1110:
	s_add_u32 s16, s10, 0x100
	s_addc_u32 s17, s11, 0
	s_add_u32 s10, s10, 0x160080
	s_addc_u32 s11, s11, 0
	v_lshl_add_u64 v[132:133], s[10:11], 0, v[168:169]
	v_lshl_add_u64 v[134:135], s[10:11], 0, v[170:171]
	s_mov_b32 s18, -2
	s_mov_b64 s[10:11], 0
	s_add_u32 vcc_lo, s10, 0x100
	s_addc_u32 vcc_hi, s11, 0
	s_add_u32 s19, s16, s10
	s_addc_u32 s24, s17, s11
	s_add_i32 s25, 0, 0x10000
	s_cmpk_eq_i32 s18, 0x54
	s_cselect_b32 s65, s61, s24
	s_cselect_b32 s24, 0, vcc_lo
	s_cselect_b32 s64, s60, s19
	s_cselect_b32 s19, 0, vcc_hi
	s_add_u32 s62, s2, s24
	v_add_u32_e32 v160, s25, v188
	s_addc_u32 s63, s3, s19
	s_add_i32 s19, 0, 0x14000
	ds_read_b128 v[136:139], v160
	ds_read_b128 v[140:143], v160 offset:1024
	ds_read_b128 v[144:147], v160 offset:2048
	ds_read_b128 v[172:175], v160 offset:3072
	v_add_u32_e32 v160, s19, v188
	ds_read_b128 v[176:179], v160
	ds_read_b128 v[180:183], v160 offset:1024
	ds_read_b128 v[184:187], v160 offset:2048
	ds_read_b128 v[208:211], v160 offset:3072
	v_lshl_add_u64 v[160:161], v[132:133], 0, s[10:11]
	s_add_i32 m0, s67, 0xc000
	ds_read_b128 v[212:215], v197
	ds_read_b128 v[216:219], v197 offset:1024
	ds_read_b128 v[220:223], v197 offset:2048
	ds_read_b128 v[224:227], v197 offset:3072
	ds_read_b128 v[228:231], v197 offset:4096
	ds_read_b128 v[232:235], v197 offset:5120
	ds_read_b128 v[236:239], v197 offset:6144
	ds_read_b128 v[240:243], v197 offset:7168
	global_load_lds_dwordx4 v[160:161], off
	v_lshl_add_u64 v[160:161], v[134:135], 0, s[10:11]
	s_add_i32 m0, s67, 0xe000
	s_nop 0
	global_load_lds_dwordx4 v[160:161], off
	s_waitcnt vmcnt(8)
	s_waitcnt lgkmcnt(0)
	s_barrier
	s_setprio 1
	s_waitcnt lgkmcnt(0)
	v_mfma_f32_16x16x32_bf16 v[16:19], v[136:139], v[212:215], 0
	v_mfma_f32_16x16x32_bf16 v[16:19], v[140:143], v[216:219], v[16:19]
	v_mfma_f32_16x16x32_bf16 v[12:15], v[144:147], v[212:215], 0
	v_mfma_f32_16x16x32_bf16 v[12:15], v[172:175], v[216:219], v[12:15]
	v_mfma_f32_16x16x32_bf16 v[56:59], v[136:139], v[220:223], 0
	v_mfma_f32_16x16x32_bf16 v[56:59], v[140:143], v[224:227], v[56:59]
	v_mfma_f32_16x16x32_bf16 v[52:55], v[144:147], v[220:223], 0
	v_mfma_f32_16x16x32_bf16 v[52:55], v[172:175], v[224:227], v[52:55]
	v_mfma_f32_16x16x32_bf16 v[88:91], v[136:139], v[228:231], 0
	v_mfma_f32_16x16x32_bf16 v[88:91], v[140:143], v[232:235], v[88:91]
	v_mfma_f32_16x16x32_bf16 v[76:79], v[144:147], v[228:231], 0
	v_mfma_f32_16x16x32_bf16 v[76:79], v[172:175], v[232:235], v[76:79]
	v_mfma_f32_16x16x32_bf16 v[112:115], v[136:139], v[236:239], 0
	v_mfma_f32_16x16x32_bf16 v[112:115], v[140:143], v[240:243], v[112:115]
	v_mfma_f32_16x16x32_bf16 v[108:111], v[144:147], v[236:239], 0
	v_mfma_f32_16x16x32_bf16 v[108:111], v[172:175], v[240:243], v[108:111]
	s_setprio 0
	s_setprio 1
	v_mfma_f32_16x16x32_bf16 v[8:11], v[176:179], v[212:215], 0
	v_mfma_f32_16x16x32_bf16 v[8:11], v[180:183], v[216:219], v[8:11]
	v_mfma_f32_16x16x32_bf16 v[4:7], v[184:187], v[212:215], 0
	v_mfma_f32_16x16x32_bf16 v[4:7], v[208:211], v[216:219], v[4:7]
	v_mfma_f32_16x16x32_bf16 v[40:43], v[176:179], v[220:223], 0
	v_mfma_f32_16x16x32_bf16 v[40:43], v[180:183], v[224:227], v[40:43]
	v_mfma_f32_16x16x32_bf16 v[36:39], v[184:187], v[220:223], 0
	v_mfma_f32_16x16x32_bf16 v[36:39], v[208:211], v[224:227], v[36:39]
	v_mfma_f32_16x16x32_bf16 v[64:67], v[176:179], v[228:231], 0
	v_mfma_f32_16x16x32_bf16 v[64:67], v[180:183], v[232:235], v[64:67]
	v_mfma_f32_16x16x32_bf16 v[60:63], v[184:187], v[228:231], 0
	v_mfma_f32_16x16x32_bf16 v[60:63], v[208:211], v[232:235], v[60:63]
	v_mfma_f32_16x16x32_bf16 v[96:99], v[176:179], v[236:239], 0
	v_mfma_f32_16x16x32_bf16 v[96:99], v[180:183], v[240:243], v[96:99]
	s_setprio 2
	s_barrier
	v_mfma_f32_16x16x32_bf16 v[92:95], v[184:187], v[236:239], 0
	v_mfma_f32_16x16x32_bf16 v[92:95], v[208:211], v[240:243], v[92:95]
	s_setprio 0
	s_add_i32 s10, s25, s66
	v_lshl_add_u64 v[160:161], s[62:63], 0, v[2:3]
	s_mov_b32 m0, s10
	ds_read_b128 v[212:215], v197 offset:16384
	ds_read_b128 v[216:219], v197 offset:17408
	ds_read_b128 v[220:223], v197 offset:18432
	ds_read_b128 v[224:227], v197 offset:19456
	ds_read_b128 v[228:231], v197 offset:20480
	ds_read_b128 v[232:235], v197 offset:21504
	ds_read_b128 v[236:239], v197 offset:22528
	ds_read_b128 v[240:243], v197 offset:23552
	global_load_lds_dwordx4 v[160:161], off
	s_add_i32 m0, s10, 0x2000
	s_add_u32 s10, s62, 0x160000
	v_lshl_add_u64 v[162:163], s[62:63], 0, v[150:151]
	s_addc_u32 s11, s63, 0
	s_add_i32 s19, s19, s66
	global_load_lds_dwordx4 v[162:163], off
	v_lshl_add_u64 v[244:245], s[10:11], 0, v[2:3]
	s_mov_b32 m0, s19
	v_lshl_add_u64 v[246:247], s[64:65], 0, v[148:149]
	global_load_lds_dwordx4 v[244:245], off
	v_lshl_add_u64 v[244:245], s[10:11], 0, v[150:151]
	s_add_i32 m0, s19, 0x2000
	s_nop 0
	global_load_lds_dwordx4 v[244:245], off
	v_lshl_add_u64 v[244:245], s[64:65], 0, v[0:1]
	s_mov_b32 m0, s67
	s_nop 0
	global_load_lds_dwordx4 v[244:245], off
	s_mov_b32 m0, s75
	s_nop 0
	global_load_lds_dwordx4 v[246:247], off
	s_waitcnt vmcnt(8)
	s_waitcnt lgkmcnt(0)
	s_barrier
; #define PG8_STAGE(bufoff, gbase, voff) do { _Pragma("unroll") for (int _i = 0; _i < 2; ++_i) \
;         __builtin_amdgcn_global_load_lds((const unsigned*)((const char*)(gbase) + (voff)[_i]), (LAS unsigned*)(lds + (bufoff) + ldsw + _i * 8192), 16, 0, 0); } while (0)
; #define PG8_LDA(dst, b, h) do { _Pragma("unroll") for (int m = 0; m < 4; ++m) _Pragma("unroll") for (int k = 0; k < 2; ++k) dst[m][k] = *(const LAS bf16x8*)(lds + PG8_SA(b, h) + aoff + m * 2048 + k * 1024); } while (0)
; #define PG8_LDB(dst, b, h) do { _Pragma("unroll") for (int n = 0; n < 2; ++n) _Pragma("unroll") for (int k = 0; k < 2; ++k) dst[n][k] = *(const LAS bf16x8*)(lds + PG8_SB(b, h) + boff + n * 2048 + k * 1024); } while (0)
; #define PG8_MMA(ai, bj, At, Bt) do { __builtin_amdgcn_s_setprio(1); _Pragma("unroll") for (int m = 0; m < 4; ++m) _Pragma("unroll") for (int n = 0; n < 2; ++n) _Pragma("unroll") for (int k = 0; k < 2; ++k) \
;         acc[ai][bj][m][n] = __builtin_amdgcn_mfma_f32_16x16x32_bf16(Bt[n][k], At[m][k], acc[ai][bj][m][n], 0, 0, 0); __builtin_amdgcn_s_setprio(0); } while (0)
; #define PG8_WAIT_V(n) asm volatile("s_waitcnt vmcnt(" #n ")" ::: "memory")
; #define PG8_WAIT_L(n) asm volatile("s_waitcnt lgkmcnt(" #n ")" ::: "memory")
; #define PG8_BAR __builtin_amdgcn_s_barrier()
; #define PG8_SCHED __builtin_amdgcn_sched_barrier(0)
; template <class Epi, class Sched, bool ALIGN_EPI = true>
; __device__ __forceinline__ void gemm_phase(LAS unsigned char* lds, const Gemm g, const Sched& S, const Epi& E) {
;     ...
;             PG8_WAIT_V(8); PG8_WAIT_L(0); PG8_BAR; PG8_MMA(1, 0, At, B0); PG8_MMA(1, 1, At, B1); PG8_BAR; PG8_SCHED;
;             PG8_LDB(B0, 1, 0); PG8_LDB(B1, 1, 1); PG8_SCHED; PG8_LDA(At, 1, 0); PG8_STAGE(PG8_SA(0, 1), a2 + hA, voffA);
;             PG8_WAIT_V(8); PG8_WAIT_L(0); PG8_BAR; PG8_MMA(0, 0, At, B0); PG8_MMA(0, 1, At, B1); PG8_BAR; PG8_SCHED;
;             PG8_LDA(At, 1, 1); PG8_STAGE(PG8_SB(1, 0), b3, voffB); PG8_STAGE(PG8_SB(1, 1), b3 + hB, voffB); PG8_STAGE(PG8_SA(1, 0), a3, voffA);
;             PG8_WAIT_V(8); PG8_WAIT_L(0); PG8_BAR; PG8_MMA(1, 0, At, B0); PG8_MMA(1, 1, At, B1); PG8_BAR; PG8_SCHED;
	s_setprio 1
	s_waitcnt lgkmcnt(0)
	v_mfma_f32_16x16x32_bf16 v[128:131], v[136:139], v[212:215], 0
	v_mfma_f32_16x16x32_bf16 v[128:131], v[140:143], v[216:219], v[128:131]
	v_mfma_f32_16x16x32_bf16 v[124:127], v[144:147], v[212:215], 0
	v_mfma_f32_16x16x32_bf16 v[124:127], v[172:175], v[216:219], v[124:127]
	v_mfma_f32_16x16x32_bf16 v[104:107], v[136:139], v[220:223], 0
	v_mfma_f32_16x16x32_bf16 v[104:107], v[140:143], v[224:227], v[104:107]
	v_mfma_f32_16x16x32_bf16 v[100:103], v[144:147], v[220:223], 0
	v_mfma_f32_16x16x32_bf16 v[100:103], v[172:175], v[224:227], v[100:103]
	v_mfma_f32_16x16x32_bf16 v[72:75], v[136:139], v[228:231], 0
	v_mfma_f32_16x16x32_bf16 v[72:75], v[140:143], v[232:235], v[72:75]
	v_mfma_f32_16x16x32_bf16 v[68:71], v[144:147], v[228:231], 0
	v_mfma_f32_16x16x32_bf16 v[68:71], v[172:175], v[232:235], v[68:71]
	v_mfma_f32_16x16x32_bf16 v[32:35], v[136:139], v[236:239], 0
	v_mfma_f32_16x16x32_bf16 v[32:35], v[140:143], v[240:243], v[32:35]
	v_mfma_f32_16x16x32_bf16 v[28:31], v[144:147], v[236:239], 0
	v_mfma_f32_16x16x32_bf16 v[28:31], v[172:175], v[240:243], v[28:31]
	s_setprio 0
	s_setprio 1
	v_mfma_f32_16x16x32_bf16 v[120:123], v[176:179], v[212:215], 0
	v_mfma_f32_16x16x32_bf16 v[120:123], v[180:183], v[216:219], v[120:123]
	v_mfma_f32_16x16x32_bf16 v[116:119], v[184:187], v[212:215], 0
	v_mfma_f32_16x16x32_bf16 v[116:119], v[208:211], v[216:219], v[116:119]
	v_mfma_f32_16x16x32_bf16 v[84:87], v[176:179], v[220:223], 0
	v_mfma_f32_16x16x32_bf16 v[84:87], v[180:183], v[224:227], v[84:87]
	v_mfma_f32_16x16x32_bf16 v[80:83], v[184:187], v[220:223], 0
	v_mfma_f32_16x16x32_bf16 v[80:83], v[208:211], v[224:227], v[80:83]
	v_mfma_f32_16x16x32_bf16 v[48:51], v[176:179], v[228:231], 0
	v_mfma_f32_16x16x32_bf16 v[48:51], v[180:183], v[232:235], v[48:51]
	v_mfma_f32_16x16x32_bf16 v[44:47], v[184:187], v[228:231], 0
	v_mfma_f32_16x16x32_bf16 v[44:47], v[208:211], v[232:235], v[44:47]
	v_mfma_f32_16x16x32_bf16 v[24:27], v[176:179], v[236:239], 0
	v_mfma_f32_16x16x32_bf16 v[24:27], v[180:183], v[240:243], v[24:27]
	s_setprio 2
	s_barrier
	v_mfma_f32_16x16x32_bf16 v[20:23], v[184:187], v[236:239], 0
	v_mfma_f32_16x16x32_bf16 v[20:23], v[208:211], v[240:243], v[20:23]
	s_setprio 0
	s_add_i32 s19, 0, 0x18000
	s_add_i32 s24, 0, 0x1c000
	v_add_u32_e32 v172, s19, v188
	v_add_u32_e32 v207, s24, v188
	ds_read_b128 v[136:139], v172
	ds_read_b128 v[140:143], v172 offset:1024
	ds_read_b128 v[144:147], v172 offset:2048
	ds_read_b128 v[172:175], v172 offset:3072
	ds_read_b128 v[176:179], v207
	ds_read_b128 v[180:183], v207 offset:1024
	ds_read_b128 v[184:187], v207 offset:2048
	ds_read_b128 v[208:211], v207 offset:3072
	s_add_u32 s10, s64, 0x160000
	s_addc_u32 s11, s65, 0
	s_mov_b32 m0, s76
	v_lshl_add_u64 v[248:249], s[10:11], 0, v[0:1]
	ds_read_b128 v[212:215], v197 offset:32768
	ds_read_b128 v[216:219], v197 offset:33792
	ds_read_b128 v[220:223], v197 offset:34816
	ds_read_b128 v[224:227], v197 offset:35840
	ds_read_b128 v[228:231], v197 offset:36864
	ds_read_b128 v[232:235], v197 offset:37888
	ds_read_b128 v[236:239], v197 offset:38912
	ds_read_b128 v[240:243], v197 offset:39936
	global_load_lds_dwordx4 v[248:249], off
	v_lshl_add_u64 v[248:249], s[10:11], 0, v[148:149]
	s_mov_b32 m0, s77
	s_nop 0
	global_load_lds_dwordx4 v[248:249], off
	s_waitcnt vmcnt(8)
	s_waitcnt lgkmcnt(0)
	s_barrier
	s_setprio 1
	s_waitcnt lgkmcnt(0)
	v_mfma_f32_16x16x32_bf16 v[16:19], v[136:139], v[212:215], v[16:19]
	v_mfma_f32_16x16x32_bf16 v[16:19], v[140:143], v[216:219], v[16:19]
	v_mfma_f32_16x16x32_bf16 v[12:15], v[144:147], v[212:215], v[12:15]
	v_mfma_f32_16x16x32_bf16 v[12:15], v[172:175], v[216:219], v[12:15]
	v_mfma_f32_16x16x32_bf16 v[56:59], v[136:139], v[220:223], v[56:59]
	v_mfma_f32_16x16x32_bf16 v[56:59], v[140:143], v[224:227], v[56:59]
	v_mfma_f32_16x16x32_bf16 v[52:55], v[144:147], v[220:223], v[52:55]
	v_mfma_f32_16x16x32_bf16 v[52:55], v[172:175], v[224:227], v[52:55]
	v_mfma_f32_16x16x32_bf16 v[88:91], v[136:139], v[228:231], v[88:91]
	v_mfma_f32_16x16x32_bf16 v[88:91], v[140:143], v[232:235], v[88:91]
	v_mfma_f32_16x16x32_bf16 v[76:79], v[144:147], v[228:231], v[76:79]
	v_mfma_f32_16x16x32_bf16 v[76:79], v[172:175], v[232:235], v[76:79]
	v_mfma_f32_16x16x32_bf16 v[112:115], v[136:139], v[236:239], v[112:115]
	v_mfma_f32_16x16x32_bf16 v[112:115], v[140:143], v[240:243], v[112:115]
	v_mfma_f32_16x16x32_bf16 v[108:111], v[144:147], v[236:239], v[108:111]
	v_mfma_f32_16x16x32_bf16 v[108:111], v[172:175], v[240:243], v[108:111]
	s_setprio 0
	s_setprio 1
	v_mfma_f32_16x16x32_bf16 v[8:11], v[176:179], v[212:215], v[8:11]
	v_mfma_f32_16x16x32_bf16 v[8:11], v[180:183], v[216:219], v[8:11]
	v_mfma_f32_16x16x32_bf16 v[4:7], v[184:187], v[212:215], v[4:7]
	v_mfma_f32_16x16x32_bf16 v[4:7], v[208:211], v[216:219], v[4:7]
	v_mfma_f32_16x16x32_bf16 v[40:43], v[176:179], v[220:223], v[40:43]
	v_mfma_f32_16x16x32_bf16 v[40:43], v[180:183], v[224:227], v[40:43]
	v_mfma_f32_16x16x32_bf16 v[36:39], v[184:187], v[220:223], v[36:39]
	v_mfma_f32_16x16x32_bf16 v[36:39], v[208:211], v[224:227], v[36:39]
	v_mfma_f32_16x16x32_bf16 v[64:67], v[176:179], v[228:231], v[64:67]
	v_mfma_f32_16x16x32_bf16 v[64:67], v[180:183], v[232:235], v[64:67]
	v_mfma_f32_16x16x32_bf16 v[60:63], v[184:187], v[228:231], v[60:63]
	v_mfma_f32_16x16x32_bf16 v[60:63], v[208:211], v[232:235], v[60:63]
	v_mfma_f32_16x16x32_bf16 v[96:99], v[176:179], v[236:239], v[96:99]
	v_mfma_f32_16x16x32_bf16 v[96:99], v[180:183], v[240:243], v[96:99]
	s_setprio 2
	s_barrier
; #define PG8_STAGE(bufoff, gbase, voff) do { _Pragma("unroll") for (int _i = 0; _i < 2; ++_i) \
;         __builtin_amdgcn_global_load_lds((const unsigned*)((const char*)(gbase) + (voff)[_i]), (LAS unsigned*)(lds + (bufoff) + ldsw + _i * 8192), 16, 0, 0); } while (0)
; #define PG8_LDA(dst, b, h) do { _Pragma("unroll") for (int m = 0; m < 4; ++m) _Pragma("unroll") for (int k = 0; k < 2; ++k) dst[m][k] = *(const LAS bf16x8*)(lds + PG8_SA(b, h) + aoff + m * 2048 + k * 1024); } while (0)
; #define PG8_LDB(dst, b, h) do { _Pragma("unroll") for (int n = 0; n < 2; ++n) _Pragma("unroll") for (int k = 0; k < 2; ++k) dst[n][k] = *(const LAS bf16x8*)(lds + PG8_SB(b, h) + boff + n * 2048 + k * 1024); } while (0)
; #define PG8_WAIT_V(n) asm volatile("s_waitcnt vmcnt(" #n ")" ::: "memory")
; #define PG8_BAR __builtin_amdgcn_s_barrier()
; template <class Epi, class Sched, bool ALIGN_EPI = true>
; __device__ __forceinline__ void gemm_phase(LAS unsigned char* lds, const Gemm g, const Sched& S, const Epi& E) {
;     ...
;         for (int t = 0; t < nt; t += 2) {
;             const bool last = (t == nt - 2);
;             const char* a1 = cA + (size_t)(t + 1) * kstep;
;             const char* a2 = last ? nA : cA + (size_t)(t + 2) * kstep; const char* b2 = last ? nB : cB + (size_t)(t + 2) * kstep;
;             const char* a3 = a2 + kstep; const char* b3 = b2 + kstep;
;             PG8_LDB(B0, 0, 0); PG8_LDB(B1, 0, 1); PG8_SCHED; PG8_LDA(At, 0, 0); PG8_STAGE(PG8_SA(1, 1), a1 + hA, voffA);
;             PG8_WAIT_V(8); PG8_WAIT_L(0); PG8_BAR; PG8_MMA(0, 0, At, B0); PG8_MMA(0, 1, At, B1); PG8_BAR; PG8_SCHED;
;             PG8_LDA(At, 0, 1); PG8_STAGE(PG8_SB(0, 0), b2, voffB); PG8_STAGE(PG8_SB(0, 1), b2 + hB, voffB); PG8_STAGE(PG8_SA(0, 0), a2, voffA);
;             PG8_WAIT_V(8); PG8_WAIT_L(0); PG8_BAR; PG8_MMA(1, 0, At, B0); PG8_MMA(1, 1, At, B1); PG8_BAR; PG8_SCHED;
;             PG8_LDB(B0, 1, 0); PG8_LDB(B1, 1, 1); PG8_SCHED; PG8_LDA(At, 1, 0); PG8_STAGE(PG8_SA(0, 1), a2 + hA, voffA);
;             PG8_WAIT_V(8); PG8_WAIT_L(0); PG8_BAR; PG8_MMA(0, 0, At, B0); PG8_MMA(0, 1, At, B1); PG8_BAR; PG8_SCHED;
;             PG8_LDA(At, 1, 1); PG8_STAGE(PG8_SB(1, 0), b3, voffB); PG8_STAGE(PG8_SB(1, 1), b3 + hB, voffB); PG8_STAGE(PG8_SA(1, 0), a3, voffA);
;             PG8_WAIT_V(8); PG8_WAIT_L(0); PG8_BAR; PG8_MMA(1, 0, At, B0); PG8_MMA(1, 1, At, B1); PG8_BAR; PG8_SCHED;
	v_mfma_f32_16x16x32_bf16 v[92:95], v[184:187], v[236:239], v[92:95]
	v_mfma_f32_16x16x32_bf16 v[92:95], v[208:211], v[240:243], v[92:95]
	s_setprio 0
	s_add_i32 s10, s19, s66
	v_lshl_add_u64 v[160:161], v[160:161], 0, s[86:87]
	s_mov_b32 m0, s10
	ds_read_b128 v[212:215], v197 offset:49152
	ds_read_b128 v[216:219], v197 offset:50176
	ds_read_b128 v[220:223], v197 offset:51200
	ds_read_b128 v[224:227], v197 offset:52224
	ds_read_b128 v[228:231], v197 offset:53248
	ds_read_b128 v[232:235], v197 offset:54272
	ds_read_b128 v[236:239], v197 offset:55296
	ds_read_b128 v[240:243], v197 offset:56320
	global_load_lds_dwordx4 v[160:161], off
	s_add_i32 m0, s10, 0x2000
	s_add_u32 s10, s62, 0x160080
	v_lshl_add_u64 v[160:161], v[162:163], 0, s[86:87]
	s_addc_u32 s11, s63, 0
	s_add_i32 s19, s24, s66
	global_load_lds_dwordx4 v[160:161], off
	v_lshl_add_u64 v[160:161], s[10:11], 0, v[2:3]
	s_mov_b32 m0, s19
	s_nop 0
	global_load_lds_dwordx4 v[160:161], off
	v_lshl_add_u64 v[160:161], s[10:11], 0, v[150:151]
	s_add_i32 m0, s19, 0x2000
	s_nop 0
	global_load_lds_dwordx4 v[160:161], off
	v_lshl_add_u64 v[160:161], v[244:245], 0, s[86:87]
	s_mov_b32 m0, s80
	s_nop 0
	global_load_lds_dwordx4 v[160:161], off
	v_lshl_add_u64 v[160:161], v[246:247], 0, s[86:87]
	s_mov_b32 m0, s81
	s_nop 0
	global_load_lds_dwordx4 v[160:161], off
	s_waitcnt vmcnt(8)
	s_waitcnt lgkmcnt(0)
	s_barrier
	s_setprio 1
	s_waitcnt lgkmcnt(0)
	v_mfma_f32_16x16x32_bf16 v[128:131], v[136:139], v[212:215], v[128:131]
	v_mfma_f32_16x16x32_bf16 v[128:131], v[140:143], v[216:219], v[128:131]
	v_mfma_f32_16x16x32_bf16 v[124:127], v[144:147], v[212:215], v[124:127]
	v_mfma_f32_16x16x32_bf16 v[124:127], v[172:175], v[216:219], v[124:127]
	v_mfma_f32_16x16x32_bf16 v[104:107], v[136:139], v[220:223], v[104:107]
	v_mfma_f32_16x16x32_bf16 v[104:107], v[140:143], v[224:227], v[104:107]
	v_mfma_f32_16x16x32_bf16 v[100:103], v[144:147], v[220:223], v[100:103]
	v_mfma_f32_16x16x32_bf16 v[100:103], v[172:175], v[224:227], v[100:103]
	v_mfma_f32_16x16x32_bf16 v[72:75], v[136:139], v[228:231], v[72:75]
	v_mfma_f32_16x16x32_bf16 v[72:75], v[140:143], v[232:235], v[72:75]
	v_mfma_f32_16x16x32_bf16 v[68:71], v[144:147], v[228:231], v[68:71]
	v_mfma_f32_16x16x32_bf16 v[68:71], v[172:175], v[232:235], v[68:71]
	v_mfma_f32_16x16x32_bf16 v[32:35], v[136:139], v[236:239], v[32:35]
	v_mfma_f32_16x16x32_bf16 v[32:35], v[140:143], v[240:243], v[32:35]
	v_mfma_f32_16x16x32_bf16 v[28:31], v[144:147], v[236:239], v[28:31]
	v_mfma_f32_16x16x32_bf16 v[28:31], v[172:175], v[240:243], v[28:31]
	s_setprio 0
	s_setprio 1
	v_mfma_f32_16x16x32_bf16 v[120:123], v[176:179], v[212:215], v[120:123]
	v_mfma_f32_16x16x32_bf16 v[120:123], v[180:183], v[216:219], v[120:123]
	v_mfma_f32_16x16x32_bf16 v[116:119], v[184:187], v[212:215], v[116:119]
	v_mfma_f32_16x16x32_bf16 v[116:119], v[208:211], v[216:219], v[116:119]
	v_mfma_f32_16x16x32_bf16 v[84:87], v[176:179], v[220:223], v[84:87]
	v_mfma_f32_16x16x32_bf16 v[84:87], v[180:183], v[224:227], v[84:87]
	v_mfma_f32_16x16x32_bf16 v[80:83], v[184:187], v[220:223], v[80:83]
	v_mfma_f32_16x16x32_bf16 v[80:83], v[208:211], v[224:227], v[80:83]
	v_mfma_f32_16x16x32_bf16 v[48:51], v[176:179], v[228:231], v[48:51]
	v_mfma_f32_16x16x32_bf16 v[48:51], v[180:183], v[232:235], v[48:51]
	v_mfma_f32_16x16x32_bf16 v[44:47], v[184:187], v[228:231], v[44:47]
	v_mfma_f32_16x16x32_bf16 v[44:47], v[208:211], v[232:235], v[44:47]
	v_mfma_f32_16x16x32_bf16 v[24:27], v[176:179], v[236:239], v[24:27]
	v_mfma_f32_16x16x32_bf16 v[24:27], v[180:183], v[240:243], v[24:27]
	s_setprio 2
	s_barrier
	v_mfma_f32_16x16x32_bf16 v[20:23], v[184:187], v[236:239], v[20:23]
	v_mfma_f32_16x16x32_bf16 v[20:23], v[208:211], v[240:243], v[20:23]
	s_setprio 0
	s_add_i32 s18, s18, 2
	s_cmpk_gt_u32 s18, 0x55
	s_mov_b64 s[10:11], vcc
	s_cbranch_scc1 .Lpeel_exit_1111
	.p2align	6
